# top-k bisection counts via per-lane VALU add-with-carry + one DPP reduction per pass; P3 row-max via permlane swaps, canonicalising maxes and dead lane-address math removed
# speedup vs baseline: 1.0119x; 1.0119x over previous
; DEVI int count_ge8(const unsigned* k, unsigned mid) {
;     ...
;     asm("v_cmp_ge_u32_e64 %0, %12, %20\n\t"
;         "v_cmp_ge_u32_e64 %1, %13, %20\n\t"
;         "v_cmp_ge_u32_e64 %2, %14, %20\n\t"
;         "v_cmp_ge_u32_e64 %3, %15, %20\n\t"
;         "v_cmp_ge_u32_e64 %4, %16, %20\n\t"
;         "v_cmp_ge_u32_e64 %5, %17, %20\n\t"
;         "v_cmp_ge_u32_e64 %6, %18, %20\n\t"
;         "v_cmp_ge_u32_e64 %7, %19, %20\n\t"
;         "s_bcnt1_i32_b64 %8, %0\n\t"
;         "s_bcnt1_i32_b64 %9, %1\n\t"
;         "s_bcnt1_i32_b64 %10, %2\n\t"
;         "s_bcnt1_i32_b64 %11, %3\n\t"
;         "s_add_i32 %8, %8, %9\n\t"
;         "s_add_i32 %10, %10, %11\n\t"
;         "s_bcnt1_i32_b64 %9, %4\n\t"
;         "s_bcnt1_i32_b64 %11, %5\n\t"
;         "s_add_i32 %8, %8, %10\n\t"
;         "s_add_i32 %9, %9, %11\n\t"
;         "s_bcnt1_i32_b64 %10, %6\n\t"
;         "s_bcnt1_i32_b64 %11, %7\n\t"
;         "s_add_i32 %8, %8, %9\n\t"
;         "s_add_i32 %10, %10, %11\n\t"
;         "s_add_i32 %8, %8, %10"
; DEVI void topk_select2(const unsigned (&kA)[64], const unsigned (&kB)[64], const bool two, const int ng, const int lim, bf16_t* mrowA, bf16_t* mrowB, const int lane) {
;     ...
;         const unsigned midA = __builtin_amdgcn_readfirstlane(pa), midB = __builtin_amdgcn_readfirstlane(pb);
;         int cA = 0, cB = 0;
;         if (!dA) {
;             cA = count_ge8(&kA[0], midA);
;             if (ng > 1) cA += count_ge8(&kA[8], midA);
;             if (ng > 2) cA += count_ge8(&kA[16], midA);
;             if (ng > 3) cA += count_ge8(&kA[24], midA);
;             if (ng > 4) cA += count_ge8(&kA[32], midA);
;             if (ng > 5) cA += count_ge8(&kA[40], midA);
;             if (ng > 6) cA += count_ge8(&kA[48], midA);
;             if (ng > 7) cA += count_ge8(&kA[56], midA);
.LBB0_492:
	v_mov_b32_e32 v235, 0
	v_mov_b32_e32 v236, 0
	v_mov_b32_e32 v237, 0
	v_mov_b32_e32 v238, 0
	s_waitcnt vmcnt(1)
	v_cndmask_b32_e64 v0, 0, 1, s[6:7]
	v_cmp_ne_u32_e64 s[0:1], 1, v0
	v_cndmask_b32_e64 v0, 0, 1, s[8:9]
	s_mov_b32 s39, 0
	s_andn2_b64 vcc, exec, s[6:7]
	v_cmp_ne_u32_e64 s[4:5], 1, v0
	s_cbranch_vccnz .LBB0_501
	s_and_b64 vcc, exec, s[4:5]
	v_cmp_ge_u32_e64 s[6:7], v90, s38
	v_cmp_ge_u32_e64 s[40:41], v91, s38
	v_cmp_ge_u32_e64 s[42:43], v86, s38
	v_cmp_ge_u32_e64 s[44:45], v87, s38
	v_addc_co_u32_e64 v235, s[6:7], 0, v235, s[6:7]
	v_cmp_ge_u32_e64 s[46:47], v88, s38
	v_addc_co_u32_e64 v236, s[40:41], 0, v236, s[40:41]
	v_cmp_ge_u32_e64 s[48:49], v89, s38
	v_addc_co_u32_e64 v235, s[42:43], 0, v235, s[42:43]
	v_cmp_ge_u32_e64 s[50:51], v84, s38
	v_addc_co_u32_e64 v236, s[44:45], 0, v236, s[44:45]
	v_cmp_ge_u32_e64 s[54:55], v85, s38
	v_addc_co_u32_e64 v235, s[46:47], 0, v235, s[46:47]
	v_addc_co_u32_e64 v236, s[48:49], 0, v236, s[48:49]
	v_addc_co_u32_e64 v235, s[50:51], 0, v235, s[50:51]
	v_addc_co_u32_e64 v236, s[54:55], 0, v236, s[54:55]
	s_mov_b32 s39, 0
	s_cbranch_vccnz .LBB0_514
	v_cmp_ge_u32_e64 s[6:7], v94, s38
	v_cmp_ge_u32_e64 s[40:41], v95, s38
	v_cmp_ge_u32_e64 s[42:43], v82, s38
	v_cmp_ge_u32_e64 s[44:45], v83, s38
	v_addc_co_u32_e64 v235, s[6:7], 0, v235, s[6:7]
	v_cmp_ge_u32_e64 s[46:47], v98, s38
	v_addc_co_u32_e64 v236, s[40:41], 0, v236, s[40:41]
	v_cmp_ge_u32_e64 s[48:49], v99, s38
	v_addc_co_u32_e64 v235, s[42:43], 0, v235, s[42:43]
	v_cmp_ge_u32_e64 s[50:51], v96, s38
	v_addc_co_u32_e64 v236, s[44:45], 0, v236, s[44:45]
	v_cmp_ge_u32_e64 s[54:55], v97, s38
	v_addc_co_u32_e64 v235, s[46:47], 0, v235, s[46:47]
	v_addc_co_u32_e64 v236, s[48:49], 0, v236, s[48:49]
	v_addc_co_u32_e64 v235, s[50:51], 0, v235, s[50:51]
	v_addc_co_u32_e64 v236, s[54:55], 0, v236, s[54:55]
	s_mov_b32 s2, 0
	s_add_i32 s39, s2, s39
	s_andn2_b64 vcc, exec, s[10:11]
	s_cbranch_vccz .LBB0_515

; DEVI int count_ge8(const unsigned* k, unsigned mid) {
;     ...
;     asm("v_cmp_ge_u32_e64 %0, %12, %20\n\t"
;         "v_cmp_ge_u32_e64 %1, %13, %20\n\t"
;         "v_cmp_ge_u32_e64 %2, %14, %20\n\t"
;         "v_cmp_ge_u32_e64 %3, %15, %20\n\t"
;         "v_cmp_ge_u32_e64 %4, %16, %20\n\t"
;         "v_cmp_ge_u32_e64 %5, %17, %20\n\t"
;         "v_cmp_ge_u32_e64 %6, %18, %20\n\t"
;         "v_cmp_ge_u32_e64 %7, %19, %20\n\t"
;         "s_bcnt1_i32_b64 %8, %0\n\t"
;         "s_bcnt1_i32_b64 %9, %1\n\t"
;         "s_bcnt1_i32_b64 %10, %2\n\t"
;         "s_bcnt1_i32_b64 %11, %3\n\t"
;         "s_add_i32 %8, %8, %9\n\t"
;         "s_add_i32 %10, %10, %11\n\t"
;         "s_bcnt1_i32_b64 %9, %4\n\t"
;         "s_bcnt1_i32_b64 %11, %5\n\t"
;         "s_add_i32 %8, %8, %10\n\t"
;         "s_add_i32 %9, %9, %11\n\t"
;         "s_bcnt1_i32_b64 %10, %6\n\t"
;         "s_bcnt1_i32_b64 %11, %7\n\t"
;         "s_add_i32 %8, %8, %9\n\t"
;         "s_add_i32 %10, %10, %11\n\t"
;         "s_add_i32 %8, %8, %10"
; DEVI void topk_select2(const unsigned (&kA)[64], const unsigned (&kB)[64], const bool two, const int ng, const int lim, bf16_t* mrowA, bf16_t* mrowB, const int lane) {
;     ...
;             cA = count_ge8(&kA[0], midA);
;             if (ng > 1) cA += count_ge8(&kA[8], midA);
;             if (ng > 2) cA += count_ge8(&kA[16], midA);
;             if (ng > 3) cA += count_ge8(&kA[24], midA);
;             if (ng > 4) cA += count_ge8(&kA[32], midA);
;             if (ng > 5) cA += count_ge8(&kA[40], midA);
;             if (ng > 6) cA += count_ge8(&kA[48], midA);
;             if (ng > 7) cA += count_ge8(&kA[56], midA);
.LBB0_496:
	v_cmp_ge_u32_e64 s[6:7], v108, s38
	v_cmp_ge_u32_e64 s[40:41], v109, s38
	v_cmp_ge_u32_e64 s[42:43], v100, s38
	v_cmp_ge_u32_e64 s[44:45], v101, s38
	v_addc_co_u32_e64 v235, s[6:7], 0, v235, s[6:7]
	v_cmp_ge_u32_e64 s[46:47], v112, s38
	v_addc_co_u32_e64 v236, s[40:41], 0, v236, s[40:41]
	v_cmp_ge_u32_e64 s[48:49], v113, s38
	v_addc_co_u32_e64 v235, s[42:43], 0, v235, s[42:43]
	v_cmp_ge_u32_e64 s[50:51], v110, s38
	v_addc_co_u32_e64 v236, s[44:45], 0, v236, s[44:45]
	v_cmp_ge_u32_e64 s[54:55], v111, s38
	v_addc_co_u32_e64 v235, s[46:47], 0, v235, s[46:47]
	v_addc_co_u32_e64 v236, s[48:49], 0, v236, s[48:49]
	v_addc_co_u32_e64 v235, s[50:51], 0, v235, s[50:51]
	v_addc_co_u32_e64 v236, s[54:55], 0, v236, s[54:55]
	s_mov_b32 s2, 0
	s_add_i32 s39, s2, s39
	s_andn2_b64 vcc, exec, s[14:15]
	s_cbranch_vccz .LBB0_517

; DEVI int count_ge8(const unsigned* k, unsigned mid) {
;     ...
;     asm("v_cmp_ge_u32_e64 %0, %12, %20\n\t"
;         "v_cmp_ge_u32_e64 %1, %13, %20\n\t"
;         "v_cmp_ge_u32_e64 %2, %14, %20\n\t"
;         "v_cmp_ge_u32_e64 %3, %15, %20\n\t"
;         "v_cmp_ge_u32_e64 %4, %16, %20\n\t"
;         "v_cmp_ge_u32_e64 %5, %17, %20\n\t"
;         "v_cmp_ge_u32_e64 %6, %18, %20\n\t"
;         "v_cmp_ge_u32_e64 %7, %19, %20\n\t"
;         "s_bcnt1_i32_b64 %8, %0\n\t"
;         "s_bcnt1_i32_b64 %9, %1\n\t"
;         "s_bcnt1_i32_b64 %10, %2\n\t"
;         "s_bcnt1_i32_b64 %11, %3\n\t"
;         "s_add_i32 %8, %8, %9\n\t"
;         "s_add_i32 %10, %10, %11\n\t"
;         "s_bcnt1_i32_b64 %9, %4\n\t"
;         "s_bcnt1_i32_b64 %11, %5\n\t"
;         "s_add_i32 %8, %8, %10\n\t"
;         "s_add_i32 %9, %9, %11\n\t"
;         "s_bcnt1_i32_b64 %10, %6\n\t"
;         "s_bcnt1_i32_b64 %11, %7\n\t"
;         "s_add_i32 %8, %8, %9\n\t"
;         "s_add_i32 %10, %10, %11\n\t"
;         "s_add_i32 %8, %8, %10"
; DEVI void topk_select2(const unsigned (&kA)[64], const unsigned (&kB)[64], const bool two, const int ng, const int lim, bf16_t* mrowA, bf16_t* mrowB, const int lane) {
;     ...
;             cA = count_ge8(&kA[0], midA);
;             if (ng > 1) cA += count_ge8(&kA[8], midA);
;             if (ng > 2) cA += count_ge8(&kA[16], midA);
;             if (ng > 3) cA += count_ge8(&kA[24], midA);
;             if (ng > 4) cA += count_ge8(&kA[32], midA);
;             if (ng > 5) cA += count_ge8(&kA[40], midA);
;             if (ng > 6) cA += count_ge8(&kA[48], midA);
;             if (ng > 7) cA += count_ge8(&kA[56], midA);
.LBB0_498:
	v_cmp_ge_u32_e64 s[6:7], v136, s38
	v_cmp_ge_u32_e64 s[40:41], v137, s38
	v_cmp_ge_u32_e64 s[42:43], v128, s38
	v_cmp_ge_u32_e64 s[44:45], v129, s38
	v_addc_co_u32_e64 v235, s[6:7], 0, v235, s[6:7]
	v_cmp_ge_u32_e64 s[46:47], v134, s38
	v_addc_co_u32_e64 v236, s[40:41], 0, v236, s[40:41]
	v_cmp_ge_u32_e64 s[48:49], v135, s38
	v_addc_co_u32_e64 v235, s[42:43], 0, v235, s[42:43]
	v_cmp_ge_u32_e64 s[50:51], v132, s38
	v_addc_co_u32_e64 v236, s[44:45], 0, v236, s[44:45]
	v_cmp_ge_u32_e64 s[54:55], v133, s38
	v_addc_co_u32_e64 v235, s[46:47], 0, v235, s[46:47]
	v_addc_co_u32_e64 v236, s[48:49], 0, v236, s[48:49]
	v_addc_co_u32_e64 v235, s[50:51], 0, v235, s[50:51]
	v_addc_co_u32_e64 v236, s[54:55], 0, v236, s[54:55]
	s_mov_b32 s2, 0
	s_add_i32 s39, s2, s39
	s_andn2_b64 vcc, exec, s[18:19]
	s_cbranch_vccz .LBB0_519

; DEVI int count_ge8(const unsigned* k, unsigned mid) {
;     ...
;     asm("v_cmp_ge_u32_e64 %0, %12, %20\n\t"
;         "v_cmp_ge_u32_e64 %1, %13, %20\n\t"
;         "v_cmp_ge_u32_e64 %2, %14, %20\n\t"
;         "v_cmp_ge_u32_e64 %3, %15, %20\n\t"
;         "v_cmp_ge_u32_e64 %4, %16, %20\n\t"
;         "v_cmp_ge_u32_e64 %5, %17, %20\n\t"
;         "v_cmp_ge_u32_e64 %6, %18, %20\n\t"
;         "v_cmp_ge_u32_e64 %7, %19, %20\n\t"
;         "s_bcnt1_i32_b64 %8, %0\n\t"
;         "s_bcnt1_i32_b64 %9, %1\n\t"
;         "s_bcnt1_i32_b64 %10, %2\n\t"
;         "s_bcnt1_i32_b64 %11, %3\n\t"
;         "s_add_i32 %8, %8, %9\n\t"
;         "s_add_i32 %10, %10, %11\n\t"
;         "s_bcnt1_i32_b64 %9, %4\n\t"
;         "s_bcnt1_i32_b64 %11, %5\n\t"
;         "s_add_i32 %8, %8, %10\n\t"
;         "s_add_i32 %9, %9, %11\n\t"
;         "s_bcnt1_i32_b64 %10, %6\n\t"
;         "s_bcnt1_i32_b64 %11, %7\n\t"
;         "s_add_i32 %8, %8, %9\n\t"
;         "s_add_i32 %10, %10, %11\n\t"
;         "s_add_i32 %8, %8, %10"
; DEVI void topk_select2(const unsigned (&kA)[64], const unsigned (&kB)[64], const bool two, const int ng, const int lim, bf16_t* mrowA, bf16_t* mrowB, const int lane) {
;     ...
;             cA = count_ge8(&kA[0], midA);
;             if (ng > 1) cA += count_ge8(&kA[8], midA);
;             if (ng > 2) cA += count_ge8(&kA[16], midA);
;             if (ng > 3) cA += count_ge8(&kA[24], midA);
;             if (ng > 4) cA += count_ge8(&kA[32], midA);
;             if (ng > 5) cA += count_ge8(&kA[40], midA);
;             if (ng > 6) cA += count_ge8(&kA[48], midA);
;             if (ng > 7) cA += count_ge8(&kA[56], midA);
;         }
;         if (!dB) {
;             cB = count_ge8(&kB[0], midB);
;             if (ng > 1) cB += count_ge8(&kB[8], midB);
;             if (ng > 2) cB += count_ge8(&kB[16], midB);
;             if (ng > 3) cB += count_ge8(&kB[24], midB);
;             if (ng > 4) cB += count_ge8(&kB[32], midB);
;             if (ng > 5) cB += count_ge8(&kB[40], midB);
;             if (ng > 6) cB += count_ge8(&kB[48], midB);
;             if (ng > 7) cB += count_ge8(&kB[56], midB);
.LBB0_500:
	v_cmp_ge_u32_e64 s[6:7], v122, s38
	v_cmp_ge_u32_e64 s[40:41], v123, s38
	v_cmp_ge_u32_e64 s[42:43], v114, s38
	v_cmp_ge_u32_e64 s[44:45], v115, s38
	v_addc_co_u32_e64 v235, s[6:7], 0, v235, s[6:7]
	v_cmp_ge_u32_e64 s[46:47], v118, s38
	v_addc_co_u32_e64 v236, s[40:41], 0, v236, s[40:41]
	v_cmp_ge_u32_e64 s[48:49], v119, s38
	v_addc_co_u32_e64 v235, s[42:43], 0, v235, s[42:43]
	v_cmp_ge_u32_e64 s[50:51], v116, s38
	v_addc_co_u32_e64 v236, s[44:45], 0, v236, s[44:45]
	v_cmp_ge_u32_e64 s[54:55], v117, s38
	v_addc_co_u32_e64 v235, s[46:47], 0, v235, s[46:47]
	v_addc_co_u32_e64 v236, s[48:49], 0, v236, s[48:49]
	v_addc_co_u32_e64 v235, s[50:51], 0, v235, s[50:51]
	v_addc_co_u32_e64 v236, s[54:55], 0, v236, s[54:55]
	s_mov_b32 s2, 0
	s_add_i32 s39, s2, s39
.LBB0_501:
	v_cndmask_b32_e64 v0, 0, 1, s[22:23]
	v_cmp_ne_u32_e64 s[6:7], 1, v0
	s_andn2_b64 vcc, exec, s[22:23]
	s_mov_b32 s22, 0
	s_cbranch_vccnz .LBB0_510
	s_and_b64 vcc, exec, s[4:5]
	v_cmp_ge_u32_e64 s[4:5], v38, s37
	v_cmp_ge_u32_e64 s[40:41], v39, s37
	v_cmp_ge_u32_e64 s[42:43], v34, s37
	v_cmp_ge_u32_e64 s[44:45], v35, s37
	v_addc_co_u32_e64 v237, s[4:5], 0, v237, s[4:5]
	v_cmp_ge_u32_e64 s[46:47], v40, s37
	v_addc_co_u32_e64 v238, s[40:41], 0, v238, s[40:41]
	v_cmp_ge_u32_e64 s[48:49], v41, s37
	v_addc_co_u32_e64 v237, s[42:43], 0, v237, s[42:43]
	v_cmp_ge_u32_e64 s[50:51], v36, s37
	v_addc_co_u32_e64 v238, s[44:45], 0, v238, s[44:45]
	v_cmp_ge_u32_e64 s[54:55], v37, s37
	v_addc_co_u32_e64 v237, s[46:47], 0, v237, s[46:47]
	v_addc_co_u32_e64 v238, s[48:49], 0, v238, s[48:49]
	v_addc_co_u32_e64 v237, s[50:51], 0, v237, s[50:51]
	v_addc_co_u32_e64 v238, s[54:55], 0, v238, s[54:55]
	s_mov_b32 s22, 0
	s_cbranch_vccnz .LBB0_520
	v_cmp_ge_u32_e64 s[4:5], v44, s37
	v_cmp_ge_u32_e64 s[40:41], v45, s37
	v_cmp_ge_u32_e64 s[42:43], v42, s37
	v_cmp_ge_u32_e64 s[44:45], v43, s37
	v_addc_co_u32_e64 v237, s[4:5], 0, v237, s[4:5]
	v_cmp_ge_u32_e64 s[46:47], v48, s37
	v_addc_co_u32_e64 v238, s[40:41], 0, v238, s[40:41]
	v_cmp_ge_u32_e64 s[48:49], v49, s37
	v_addc_co_u32_e64 v237, s[42:43], 0, v237, s[42:43]
	v_cmp_ge_u32_e64 s[50:51], v46, s37
	v_addc_co_u32_e64 v238, s[44:45], 0, v238, s[44:45]
	v_cmp_ge_u32_e64 s[54:55], v47, s37
	v_addc_co_u32_e64 v237, s[46:47], 0, v237, s[46:47]
	v_addc_co_u32_e64 v238, s[48:49], 0, v238, s[48:49]
	v_addc_co_u32_e64 v237, s[50:51], 0, v237, s[50:51]
	v_addc_co_u32_e64 v238, s[54:55], 0, v238, s[54:55]
	s_mov_b32 s2, 0
	s_add_i32 s22, s2, s22
	s_andn2_b64 vcc, exec, s[10:11]
	s_cbranch_vccz .LBB0_521

; DEVI int count_ge8(const unsigned* k, unsigned mid) {
;     ...
;     asm("v_cmp_ge_u32_e64 %0, %12, %20\n\t"
;         "v_cmp_ge_u32_e64 %1, %13, %20\n\t"
;         "v_cmp_ge_u32_e64 %2, %14, %20\n\t"
;         "v_cmp_ge_u32_e64 %3, %15, %20\n\t"
;         "v_cmp_ge_u32_e64 %4, %16, %20\n\t"
;         "v_cmp_ge_u32_e64 %5, %17, %20\n\t"
;         "v_cmp_ge_u32_e64 %6, %18, %20\n\t"
;         "v_cmp_ge_u32_e64 %7, %19, %20\n\t"
;         "s_bcnt1_i32_b64 %8, %0\n\t"
;         "s_bcnt1_i32_b64 %9, %1\n\t"
;         "s_bcnt1_i32_b64 %10, %2\n\t"
;         "s_bcnt1_i32_b64 %11, %3\n\t"
;         "s_add_i32 %8, %8, %9\n\t"
;         "s_add_i32 %10, %10, %11\n\t"
;         "s_bcnt1_i32_b64 %9, %4\n\t"
;         "s_bcnt1_i32_b64 %11, %5\n\t"
;         "s_add_i32 %8, %8, %10\n\t"
;         "s_add_i32 %9, %9, %11\n\t"
;         "s_bcnt1_i32_b64 %10, %6\n\t"
;         "s_bcnt1_i32_b64 %11, %7\n\t"
;         "s_add_i32 %8, %8, %9\n\t"
;         "s_add_i32 %10, %10, %11\n\t"
;         "s_add_i32 %8, %8, %10"
; DEVI void topk_select2(const unsigned (&kA)[64], const unsigned (&kB)[64], const bool two, const int ng, const int lim, bf16_t* mrowA, bf16_t* mrowB, const int lane) {
;     ...
;             cB = count_ge8(&kB[0], midB);
;             if (ng > 1) cB += count_ge8(&kB[8], midB);
;             if (ng > 2) cB += count_ge8(&kB[16], midB);
;             if (ng > 3) cB += count_ge8(&kB[24], midB);
;             if (ng > 4) cB += count_ge8(&kB[32], midB);
;             if (ng > 5) cB += count_ge8(&kB[40], midB);
;             if (ng > 6) cB += count_ge8(&kB[48], midB);
;             if (ng > 7) cB += count_ge8(&kB[56], midB);
.LBB0_505:
	v_cmp_ge_u32_e64 s[4:5], v60, s37
	v_cmp_ge_u32_e64 s[40:41], v61, s37
	v_cmp_ge_u32_e64 s[42:43], v58, s37
	v_cmp_ge_u32_e64 s[44:45], v59, s37
	v_addc_co_u32_e64 v237, s[4:5], 0, v237, s[4:5]
	v_cmp_ge_u32_e64 s[46:47], v64, s37
	v_addc_co_u32_e64 v238, s[40:41], 0, v238, s[40:41]
	v_cmp_ge_u32_e64 s[48:49], v65, s37
	v_addc_co_u32_e64 v237, s[42:43], 0, v237, s[42:43]
	v_cmp_ge_u32_e64 s[50:51], v62, s37
	v_addc_co_u32_e64 v238, s[44:45], 0, v238, s[44:45]
	v_cmp_ge_u32_e64 s[54:55], v63, s37
	v_addc_co_u32_e64 v237, s[46:47], 0, v237, s[46:47]
	v_addc_co_u32_e64 v238, s[48:49], 0, v238, s[48:49]
	v_addc_co_u32_e64 v237, s[50:51], 0, v237, s[50:51]
	v_addc_co_u32_e64 v238, s[54:55], 0, v238, s[54:55]
	s_mov_b32 s2, 0
	s_add_i32 s22, s2, s22
	s_andn2_b64 vcc, exec, s[14:15]
	s_cbranch_vccz .LBB0_523

; DEVI int count_ge8(const unsigned* k, unsigned mid) {
;     ...
;     asm("v_cmp_ge_u32_e64 %0, %12, %20\n\t"
;         "v_cmp_ge_u32_e64 %1, %13, %20\n\t"
;         "v_cmp_ge_u32_e64 %2, %14, %20\n\t"
;         "v_cmp_ge_u32_e64 %3, %15, %20\n\t"
;         "v_cmp_ge_u32_e64 %4, %16, %20\n\t"
;         "v_cmp_ge_u32_e64 %5, %17, %20\n\t"
;         "v_cmp_ge_u32_e64 %6, %18, %20\n\t"
;         "v_cmp_ge_u32_e64 %7, %19, %20\n\t"
;         "s_bcnt1_i32_b64 %8, %0\n\t"
;         "s_bcnt1_i32_b64 %9, %1\n\t"
;         "s_bcnt1_i32_b64 %10, %2\n\t"
;         "s_bcnt1_i32_b64 %11, %3\n\t"
;         "s_add_i32 %8, %8, %9\n\t"
;         "s_add_i32 %10, %10, %11\n\t"
;         "s_bcnt1_i32_b64 %9, %4\n\t"
;         "s_bcnt1_i32_b64 %11, %5\n\t"
;         "s_add_i32 %8, %8, %10\n\t"
;         "s_add_i32 %9, %9, %11\n\t"
;         "s_bcnt1_i32_b64 %10, %6\n\t"
;         "s_bcnt1_i32_b64 %11, %7\n\t"
;         "s_add_i32 %8, %8, %9\n\t"
;         "s_add_i32 %10, %10, %11\n\t"
;         "s_add_i32 %8, %8, %10"
; DEVI void topk_select2(const unsigned (&kA)[64], const unsigned (&kB)[64], const bool two, const int ng, const int lim, bf16_t* mrowA, bf16_t* mrowB, const int lane) {
;     ...
;             cB = count_ge8(&kB[0], midB);
;             if (ng > 1) cB += count_ge8(&kB[8], midB);
;             if (ng > 2) cB += count_ge8(&kB[16], midB);
;             if (ng > 3) cB += count_ge8(&kB[24], midB);
;             if (ng > 4) cB += count_ge8(&kB[32], midB);
;             if (ng > 5) cB += count_ge8(&kB[40], midB);
;             if (ng > 6) cB += count_ge8(&kB[48], midB);
;             if (ng > 7) cB += count_ge8(&kB[56], midB);
.LBB0_507:
	v_cmp_ge_u32_e64 s[4:5], v74, s37
	v_cmp_ge_u32_e64 s[40:41], v75, s37
	v_cmp_ge_u32_e64 s[42:43], v68, s37
	v_cmp_ge_u32_e64 s[44:45], v69, s37
	v_addc_co_u32_e64 v237, s[4:5], 0, v237, s[4:5]
	v_cmp_ge_u32_e64 s[46:47], v70, s37
	v_addc_co_u32_e64 v238, s[40:41], 0, v238, s[40:41]
	v_cmp_ge_u32_e64 s[48:49], v71, s37
	v_addc_co_u32_e64 v237, s[42:43], 0, v237, s[42:43]
	v_cmp_ge_u32_e64 s[50:51], v30, s37
	v_addc_co_u32_e64 v238, s[44:45], 0, v238, s[44:45]
	v_cmp_ge_u32_e64 s[54:55], v31, s37
	v_addc_co_u32_e64 v237, s[46:47], 0, v237, s[46:47]
	v_addc_co_u32_e64 v238, s[48:49], 0, v238, s[48:49]
	v_addc_co_u32_e64 v237, s[50:51], 0, v237, s[50:51]
	v_addc_co_u32_e64 v238, s[54:55], 0, v238, s[54:55]
	s_mov_b32 s2, 0
	s_add_i32 s22, s2, s22
	s_andn2_b64 vcc, exec, s[18:19]
	s_cbranch_vccz .LBB0_525

; DEVI int count_ge8(const unsigned* k, unsigned mid) {
;     ...
;     asm("v_cmp_ge_u32_e64 %0, %12, %20\n\t"
;         "v_cmp_ge_u32_e64 %1, %13, %20\n\t"
;         "v_cmp_ge_u32_e64 %2, %14, %20\n\t"
;         "v_cmp_ge_u32_e64 %3, %15, %20\n\t"
;         "v_cmp_ge_u32_e64 %4, %16, %20\n\t"
;         "v_cmp_ge_u32_e64 %5, %17, %20\n\t"
;         "v_cmp_ge_u32_e64 %6, %18, %20\n\t"
;         "v_cmp_ge_u32_e64 %7, %19, %20\n\t"
;         "s_bcnt1_i32_b64 %8, %0\n\t"
;         "s_bcnt1_i32_b64 %9, %1\n\t"
;         "s_bcnt1_i32_b64 %10, %2\n\t"
;         "s_bcnt1_i32_b64 %11, %3\n\t"
;         "s_add_i32 %8, %8, %9\n\t"
;         "s_add_i32 %10, %10, %11\n\t"
;         "s_bcnt1_i32_b64 %9, %4\n\t"
;         "s_bcnt1_i32_b64 %11, %5\n\t"
;         "s_add_i32 %8, %8, %10\n\t"
;         "s_add_i32 %9, %9, %11\n\t"
;         "s_bcnt1_i32_b64 %10, %6\n\t"
;         "s_bcnt1_i32_b64 %11, %7\n\t"
;         "s_add_i32 %8, %8, %9\n\t"
;         "s_add_i32 %10, %10, %11\n\t"
;         "s_add_i32 %8, %8, %10"
; DEVI void topk_select2(const unsigned (&kA)[64], const unsigned (&kB)[64], const bool two, const int ng, const int lim, bf16_t* mrowA, bf16_t* mrowB, const int lane) {
;     ...
;             cB = count_ge8(&kB[0], midB);
;             if (ng > 1) cB += count_ge8(&kB[8], midB);
;             if (ng > 2) cB += count_ge8(&kB[16], midB);
;             if (ng > 3) cB += count_ge8(&kB[24], midB);
;             if (ng > 4) cB += count_ge8(&kB[32], midB);
;             if (ng > 5) cB += count_ge8(&kB[40], midB);
;             if (ng > 6) cB += count_ge8(&kB[48], midB);
;             if (ng > 7) cB += count_ge8(&kB[56], midB);
;         }
;         if (!dA) {
;             if (cA >= 256) { loA = midA; clA = cA; } else { hiA = midA; chA = cA; }
;             if (cA == 256) { TA = midA; needA = 0; dA = true; }
;             else if (hiA - loA == 1u) { TA = loA; needA = (clA == 256) ? 0 : (256 - chA); dA = true; }
.LBB0_509:
	v_cmp_ge_u32_e64 s[4:5], v24, s37
	v_cmp_ge_u32_e64 s[40:41], v25, s37
	v_cmp_ge_u32_e64 s[42:43], v18, s37
	v_cmp_ge_u32_e64 s[44:45], v19, s37
	v_addc_co_u32_e64 v237, s[4:5], 0, v237, s[4:5]
	v_cmp_ge_u32_e64 s[46:47], v20, s37
	v_addc_co_u32_e64 v238, s[40:41], 0, v238, s[40:41]
	v_cmp_ge_u32_e64 s[48:49], v21, s37
	v_addc_co_u32_e64 v237, s[42:43], 0, v237, s[42:43]
	v_cmp_ge_u32_e64 s[50:51], v16, s37
	v_addc_co_u32_e64 v238, s[44:45], 0, v238, s[44:45]
	v_cmp_ge_u32_e64 s[54:55], v17, s37
	v_addc_co_u32_e64 v237, s[46:47], 0, v237, s[46:47]
	v_addc_co_u32_e64 v238, s[48:49], 0, v238, s[48:49]
	v_addc_co_u32_e64 v237, s[50:51], 0, v237, s[50:51]
	v_addc_co_u32_e64 v238, s[54:55], 0, v238, s[54:55]
	s_mov_b32 s2, 0
	s_add_i32 s22, s2, s22
.LBB0_510:
	v_add_u32_e32 v235, v235, v236
	v_add_u32_e32 v237, v237, v238
	v_lshl_add_u32 v239, v237, 16, v235
	s_nop 1
	v_add_u32_dpp v239, v239, v239 quad_perm:[1,0,3,2] row_mask:0xf bank_mask:0xf bound_ctrl:1
	s_nop 1
	v_add_u32_dpp v239, v239, v239 quad_perm:[2,3,0,1] row_mask:0xf bank_mask:0xf bound_ctrl:1
	s_nop 1
	v_add_u32_dpp v239, v239, v239 row_half_mirror row_mask:0xf bank_mask:0xf bound_ctrl:1
	s_nop 1
	v_add_u32_dpp v239, v239, v239 row_mirror row_mask:0xf bank_mask:0xf bound_ctrl:1
	s_nop 1
	v_readlane_b32 s2, v239, 0
	v_readlane_b32 s3, v239, 16
	v_readlane_b32 s23, v239, 32
	v_readlane_b32 s56, v239, 48
	s_add_i32 s2, s2, s3
	s_add_i32 s23, s23, s56
	s_add_i32 s2, s2, s23
	s_and_b32 s39, s2, 0xffff
	s_lshr_b32 s22, s2, 16
	s_and_b64 vcc, exec, s[0:1]
	s_mov_b64 s[4:5], -1
	s_cbranch_vccnz .LBB0_526
	s_cmpk_gt_i32 s39, 0xff
	s_cselect_b32 s31, s31, s39
	s_cselect_b32 s24, s39, s24
	s_cselect_b32 s26, s26, s38
	s_cselect_b32 s29, s38, s29
	s_cmpk_eq_i32 s39, 0x100
	s_cbranch_scc1 .LBB0_531
	s_sub_i32 s0, s26, s29
	s_cmp_lg_u32 s0, 1
	s_mov_b64 s[0:1], 0
	s_cbranch_scc1 .LBB0_527
	s_sub_i32 s0, 0x100, s31
	s_cmpk_lg_i32 s24, 0x100
	s_cselect_b32 s72, s0, 0
	s_mov_b64 s[0:1], -1
	s_mov_b32 s73, s29
	s_and_b64 vcc, exec, s[6:7]
	s_cbranch_vccnz .LBB0_485
	s_branch .LBB0_528

; DEVI int count_ge8(const unsigned* k, unsigned mid) {
;     ...
;     asm("v_cmp_ge_u32_e64 %0, %12, %20\n\t"
;         "v_cmp_ge_u32_e64 %1, %13, %20\n\t"
;         "v_cmp_ge_u32_e64 %2, %14, %20\n\t"
;         "v_cmp_ge_u32_e64 %3, %15, %20\n\t"
;         "v_cmp_ge_u32_e64 %4, %16, %20\n\t"
;         "v_cmp_ge_u32_e64 %5, %17, %20\n\t"
;         "v_cmp_ge_u32_e64 %6, %18, %20\n\t"
;         "v_cmp_ge_u32_e64 %7, %19, %20\n\t"
;         "s_bcnt1_i32_b64 %8, %0\n\t"
;         "s_bcnt1_i32_b64 %9, %1\n\t"
;         "s_bcnt1_i32_b64 %10, %2\n\t"
;         "s_bcnt1_i32_b64 %11, %3\n\t"
;         "s_add_i32 %8, %8, %9\n\t"
;         "s_add_i32 %10, %10, %11\n\t"
;         "s_bcnt1_i32_b64 %9, %4\n\t"
;         "s_bcnt1_i32_b64 %11, %5\n\t"
;         "s_add_i32 %8, %8, %10\n\t"
;         "s_add_i32 %9, %9, %11\n\t"
;         "s_bcnt1_i32_b64 %10, %6\n\t"
;         "s_bcnt1_i32_b64 %11, %7\n\t"
;         "s_add_i32 %8, %8, %9\n\t"
;         "s_add_i32 %10, %10, %11\n\t"
;         "s_add_i32 %8, %8, %10"
; DEVI void topk_select2(const unsigned (&kA)[64], const unsigned (&kB)[64], const bool two, const int ng, const int lim, bf16_t* mrowA, bf16_t* mrowB, const int lane) {
;     ...
;             cA = count_ge8(&kA[0], midA);
;             if (ng > 1) cA += count_ge8(&kA[8], midA);
;             if (ng > 2) cA += count_ge8(&kA[16], midA);
;             if (ng > 3) cA += count_ge8(&kA[24], midA);
;             if (ng > 4) cA += count_ge8(&kA[32], midA);
;             if (ng > 5) cA += count_ge8(&kA[40], midA);
;             if (ng > 6) cA += count_ge8(&kA[48], midA);
;             if (ng > 7) cA += count_ge8(&kA[56], midA);
.LBB0_515:
	v_cmp_ge_u32_e64 s[6:7], v102, s38
	v_cmp_ge_u32_e64 s[40:41], v103, s38
	v_cmp_ge_u32_e64 s[42:43], v92, s38
	v_cmp_ge_u32_e64 s[44:45], v93, s38
	v_addc_co_u32_e64 v235, s[6:7], 0, v235, s[6:7]
	v_cmp_ge_u32_e64 s[46:47], v106, s38
	v_addc_co_u32_e64 v236, s[40:41], 0, v236, s[40:41]
	v_cmp_ge_u32_e64 s[48:49], v107, s38
	v_addc_co_u32_e64 v235, s[42:43], 0, v235, s[42:43]
	v_cmp_ge_u32_e64 s[50:51], v104, s38
	v_addc_co_u32_e64 v236, s[44:45], 0, v236, s[44:45]
	v_cmp_ge_u32_e64 s[54:55], v105, s38
	v_addc_co_u32_e64 v235, s[46:47], 0, v235, s[46:47]
	v_addc_co_u32_e64 v236, s[48:49], 0, v236, s[48:49]
	v_addc_co_u32_e64 v235, s[50:51], 0, v235, s[50:51]
	v_addc_co_u32_e64 v236, s[54:55], 0, v236, s[54:55]
	s_mov_b32 s2, 0
	s_add_i32 s39, s2, s39
	s_andn2_b64 vcc, exec, s[12:13]
	s_cbranch_vccz .LBB0_496

; DEVI int count_ge8(const unsigned* k, unsigned mid) {
;     ...
;     asm("v_cmp_ge_u32_e64 %0, %12, %20\n\t"
;         "v_cmp_ge_u32_e64 %1, %13, %20\n\t"
;         "v_cmp_ge_u32_e64 %2, %14, %20\n\t"
;         "v_cmp_ge_u32_e64 %3, %15, %20\n\t"
;         "v_cmp_ge_u32_e64 %4, %16, %20\n\t"
;         "v_cmp_ge_u32_e64 %5, %17, %20\n\t"
;         "v_cmp_ge_u32_e64 %6, %18, %20\n\t"
;         "v_cmp_ge_u32_e64 %7, %19, %20\n\t"
;         "s_bcnt1_i32_b64 %8, %0\n\t"
;         "s_bcnt1_i32_b64 %9, %1\n\t"
;         "s_bcnt1_i32_b64 %10, %2\n\t"
;         "s_bcnt1_i32_b64 %11, %3\n\t"
;         "s_add_i32 %8, %8, %9\n\t"
;         "s_add_i32 %10, %10, %11\n\t"
;         "s_bcnt1_i32_b64 %9, %4\n\t"
;         "s_bcnt1_i32_b64 %11, %5\n\t"
;         "s_add_i32 %8, %8, %10\n\t"
;         "s_add_i32 %9, %9, %11\n\t"
;         "s_bcnt1_i32_b64 %10, %6\n\t"
;         "s_bcnt1_i32_b64 %11, %7\n\t"
;         "s_add_i32 %8, %8, %9\n\t"
;         "s_add_i32 %10, %10, %11\n\t"
;         "s_add_i32 %8, %8, %10"
; DEVI void topk_select2(const unsigned (&kA)[64], const unsigned (&kB)[64], const bool two, const int ng, const int lim, bf16_t* mrowA, bf16_t* mrowB, const int lane) {
;     ...
;             cA = count_ge8(&kA[0], midA);
;             if (ng > 1) cA += count_ge8(&kA[8], midA);
;             if (ng > 2) cA += count_ge8(&kA[16], midA);
;             if (ng > 3) cA += count_ge8(&kA[24], midA);
;             if (ng > 4) cA += count_ge8(&kA[32], midA);
;             if (ng > 5) cA += count_ge8(&kA[40], midA);
;             if (ng > 6) cA += count_ge8(&kA[48], midA);
;             if (ng > 7) cA += count_ge8(&kA[56], midA);
.LBB0_517:
	v_cmp_ge_u32_e64 s[6:7], v144, s38
	v_cmp_ge_u32_e64 s[40:41], v145, s38
	v_cmp_ge_u32_e64 s[42:43], v142, s38
	v_cmp_ge_u32_e64 s[44:45], v143, s38
	v_addc_co_u32_e64 v235, s[6:7], 0, v235, s[6:7]
	v_cmp_ge_u32_e64 s[46:47], v140, s38
	v_addc_co_u32_e64 v236, s[40:41], 0, v236, s[40:41]
	v_cmp_ge_u32_e64 s[48:49], v141, s38
	v_addc_co_u32_e64 v235, s[42:43], 0, v235, s[42:43]
	v_cmp_ge_u32_e64 s[50:51], v138, s38
	v_addc_co_u32_e64 v236, s[44:45], 0, v236, s[44:45]
	v_cmp_ge_u32_e64 s[54:55], v139, s38
	v_addc_co_u32_e64 v235, s[46:47], 0, v235, s[46:47]
	v_addc_co_u32_e64 v236, s[48:49], 0, v236, s[48:49]
	v_addc_co_u32_e64 v235, s[50:51], 0, v235, s[50:51]
	v_addc_co_u32_e64 v236, s[54:55], 0, v236, s[54:55]
	s_mov_b32 s2, 0
	s_add_i32 s39, s2, s39
	s_andn2_b64 vcc, exec, s[16:17]
	s_cbranch_vccz .LBB0_498

; DEVI int count_ge8(const unsigned* k, unsigned mid) {
;     ...
;     asm("v_cmp_ge_u32_e64 %0, %12, %20\n\t"
;         "v_cmp_ge_u32_e64 %1, %13, %20\n\t"
;         "v_cmp_ge_u32_e64 %2, %14, %20\n\t"
;         "v_cmp_ge_u32_e64 %3, %15, %20\n\t"
;         "v_cmp_ge_u32_e64 %4, %16, %20\n\t"
;         "v_cmp_ge_u32_e64 %5, %17, %20\n\t"
;         "v_cmp_ge_u32_e64 %6, %18, %20\n\t"
;         "v_cmp_ge_u32_e64 %7, %19, %20\n\t"
;         "s_bcnt1_i32_b64 %8, %0\n\t"
;         "s_bcnt1_i32_b64 %9, %1\n\t"
;         "s_bcnt1_i32_b64 %10, %2\n\t"
;         "s_bcnt1_i32_b64 %11, %3\n\t"
;         "s_add_i32 %8, %8, %9\n\t"
;         "s_add_i32 %10, %10, %11\n\t"
;         "s_bcnt1_i32_b64 %9, %4\n\t"
;         "s_bcnt1_i32_b64 %11, %5\n\t"
;         "s_add_i32 %8, %8, %10\n\t"
;         "s_add_i32 %9, %9, %11\n\t"
;         "s_bcnt1_i32_b64 %10, %6\n\t"
;         "s_bcnt1_i32_b64 %11, %7\n\t"
;         "s_add_i32 %8, %8, %9\n\t"
;         "s_add_i32 %10, %10, %11\n\t"
;         "s_add_i32 %8, %8, %10"
; DEVI void topk_select2(const unsigned (&kA)[64], const unsigned (&kB)[64], const bool two, const int ng, const int lim, bf16_t* mrowA, bf16_t* mrowB, const int lane) {
;     ...
;             cA = count_ge8(&kA[0], midA);
;             if (ng > 1) cA += count_ge8(&kA[8], midA);
;             if (ng > 2) cA += count_ge8(&kA[16], midA);
;             if (ng > 3) cA += count_ge8(&kA[24], midA);
;             if (ng > 4) cA += count_ge8(&kA[32], midA);
;             if (ng > 5) cA += count_ge8(&kA[40], midA);
;             if (ng > 6) cA += count_ge8(&kA[48], midA);
;             if (ng > 7) cA += count_ge8(&kA[56], midA);
.LBB0_519:
	v_cmp_ge_u32_e64 s[6:7], v130, s38
	v_cmp_ge_u32_e64 s[40:41], v131, s38
	v_cmp_ge_u32_e64 s[42:43], v120, s38
	v_cmp_ge_u32_e64 s[44:45], v121, s38
	v_addc_co_u32_e64 v235, s[6:7], 0, v235, s[6:7]
	v_cmp_ge_u32_e64 s[46:47], v126, s38
	v_addc_co_u32_e64 v236, s[40:41], 0, v236, s[40:41]
	v_cmp_ge_u32_e64 s[48:49], v127, s38
	v_addc_co_u32_e64 v235, s[42:43], 0, v235, s[42:43]
	v_cmp_ge_u32_e64 s[50:51], v124, s38
	v_addc_co_u32_e64 v236, s[44:45], 0, v236, s[44:45]
	v_cmp_ge_u32_e64 s[54:55], v125, s38
	v_addc_co_u32_e64 v235, s[46:47], 0, v235, s[46:47]
	v_addc_co_u32_e64 v236, s[48:49], 0, v236, s[48:49]
	v_addc_co_u32_e64 v235, s[50:51], 0, v235, s[50:51]
	v_addc_co_u32_e64 v236, s[54:55], 0, v236, s[54:55]
	s_mov_b32 s2, 0
	s_add_i32 s39, s2, s39
	s_andn2_b64 vcc, exec, s[20:21]
	s_cbranch_vccz .LBB0_500
	s_branch .LBB0_501

; DEVI int count_ge8(const unsigned* k, unsigned mid) {
;     ...
;     asm("v_cmp_ge_u32_e64 %0, %12, %20\n\t"
;         "v_cmp_ge_u32_e64 %1, %13, %20\n\t"
;         "v_cmp_ge_u32_e64 %2, %14, %20\n\t"
;         "v_cmp_ge_u32_e64 %3, %15, %20\n\t"
;         "v_cmp_ge_u32_e64 %4, %16, %20\n\t"
;         "v_cmp_ge_u32_e64 %5, %17, %20\n\t"
;         "v_cmp_ge_u32_e64 %6, %18, %20\n\t"
;         "v_cmp_ge_u32_e64 %7, %19, %20\n\t"
;         "s_bcnt1_i32_b64 %8, %0\n\t"
;         "s_bcnt1_i32_b64 %9, %1\n\t"
;         "s_bcnt1_i32_b64 %10, %2\n\t"
;         "s_bcnt1_i32_b64 %11, %3\n\t"
;         "s_add_i32 %8, %8, %9\n\t"
;         "s_add_i32 %10, %10, %11\n\t"
;         "s_bcnt1_i32_b64 %9, %4\n\t"
;         "s_bcnt1_i32_b64 %11, %5\n\t"
;         "s_add_i32 %8, %8, %10\n\t"
;         "s_add_i32 %9, %9, %11\n\t"
;         "s_bcnt1_i32_b64 %10, %6\n\t"
;         "s_bcnt1_i32_b64 %11, %7\n\t"
;         "s_add_i32 %8, %8, %9\n\t"
;         "s_add_i32 %10, %10, %11\n\t"
;         "s_add_i32 %8, %8, %10"
; DEVI void topk_select2(const unsigned (&kA)[64], const unsigned (&kB)[64], const bool two, const int ng, const int lim, bf16_t* mrowA, bf16_t* mrowB, const int lane) {
;     ...
;             cB = count_ge8(&kB[0], midB);
;             if (ng > 1) cB += count_ge8(&kB[8], midB);
;             if (ng > 2) cB += count_ge8(&kB[16], midB);
;             if (ng > 3) cB += count_ge8(&kB[24], midB);
;             if (ng > 4) cB += count_ge8(&kB[32], midB);
;             if (ng > 5) cB += count_ge8(&kB[40], midB);
;             if (ng > 6) cB += count_ge8(&kB[48], midB);
;             if (ng > 7) cB += count_ge8(&kB[56], midB);
.LBB0_521:
	v_cmp_ge_u32_e64 s[4:5], v52, s37
	v_cmp_ge_u32_e64 s[40:41], v53, s37
	v_cmp_ge_u32_e64 s[42:43], v50, s37
	v_cmp_ge_u32_e64 s[44:45], v51, s37
	v_addc_co_u32_e64 v237, s[4:5], 0, v237, s[4:5]
	v_cmp_ge_u32_e64 s[46:47], v56, s37
	v_addc_co_u32_e64 v238, s[40:41], 0, v238, s[40:41]
	v_cmp_ge_u32_e64 s[48:49], v57, s37
	v_addc_co_u32_e64 v237, s[42:43], 0, v237, s[42:43]
	v_cmp_ge_u32_e64 s[50:51], v54, s37
	v_addc_co_u32_e64 v238, s[44:45], 0, v238, s[44:45]
	v_cmp_ge_u32_e64 s[54:55], v55, s37
	v_addc_co_u32_e64 v237, s[46:47], 0, v237, s[46:47]
	v_addc_co_u32_e64 v238, s[48:49], 0, v238, s[48:49]
	v_addc_co_u32_e64 v237, s[50:51], 0, v237, s[50:51]
	v_addc_co_u32_e64 v238, s[54:55], 0, v238, s[54:55]
	s_mov_b32 s2, 0
	s_add_i32 s22, s2, s22
	s_andn2_b64 vcc, exec, s[12:13]
	s_cbranch_vccz .LBB0_505

; DEVI int count_ge8(const unsigned* k, unsigned mid) {
;     ...
;     asm("v_cmp_ge_u32_e64 %0, %12, %20\n\t"
;         "v_cmp_ge_u32_e64 %1, %13, %20\n\t"
;         "v_cmp_ge_u32_e64 %2, %14, %20\n\t"
;         "v_cmp_ge_u32_e64 %3, %15, %20\n\t"
;         "v_cmp_ge_u32_e64 %4, %16, %20\n\t"
;         "v_cmp_ge_u32_e64 %5, %17, %20\n\t"
;         "v_cmp_ge_u32_e64 %6, %18, %20\n\t"
;         "v_cmp_ge_u32_e64 %7, %19, %20\n\t"
;         "s_bcnt1_i32_b64 %8, %0\n\t"
;         "s_bcnt1_i32_b64 %9, %1\n\t"
;         "s_bcnt1_i32_b64 %10, %2\n\t"
;         "s_bcnt1_i32_b64 %11, %3\n\t"
;         "s_add_i32 %8, %8, %9\n\t"
;         "s_add_i32 %10, %10, %11\n\t"
;         "s_bcnt1_i32_b64 %9, %4\n\t"
;         "s_bcnt1_i32_b64 %11, %5\n\t"
;         "s_add_i32 %8, %8, %10\n\t"
;         "s_add_i32 %9, %9, %11\n\t"
;         "s_bcnt1_i32_b64 %10, %6\n\t"
;         "s_bcnt1_i32_b64 %11, %7\n\t"
;         "s_add_i32 %8, %8, %9\n\t"
;         "s_add_i32 %10, %10, %11\n\t"
;         "s_add_i32 %8, %8, %10"
; DEVI void topk_select2(const unsigned (&kA)[64], const unsigned (&kB)[64], const bool two, const int ng, const int lim, bf16_t* mrowA, bf16_t* mrowB, const int lane) {
;     ...
;             cB = count_ge8(&kB[0], midB);
;             if (ng > 1) cB += count_ge8(&kB[8], midB);
;             if (ng > 2) cB += count_ge8(&kB[16], midB);
;             if (ng > 3) cB += count_ge8(&kB[24], midB);
;             if (ng > 4) cB += count_ge8(&kB[32], midB);
;             if (ng > 5) cB += count_ge8(&kB[40], midB);
;             if (ng > 6) cB += count_ge8(&kB[48], midB);
;             if (ng > 7) cB += count_ge8(&kB[56], midB);
.LBB0_523:
	v_cmp_ge_u32_e64 s[4:5], v80, s37
	v_cmp_ge_u32_e64 s[40:41], v81, s37
	v_cmp_ge_u32_e64 s[42:43], v78, s37
	v_cmp_ge_u32_e64 s[44:45], v79, s37
	v_addc_co_u32_e64 v237, s[4:5], 0, v237, s[4:5]
	v_cmp_ge_u32_e64 s[46:47], v76, s37
	v_addc_co_u32_e64 v238, s[40:41], 0, v238, s[40:41]
	v_cmp_ge_u32_e64 s[48:49], v77, s37
	v_addc_co_u32_e64 v237, s[42:43], 0, v237, s[42:43]
	v_cmp_ge_u32_e64 s[50:51], v72, s37
	v_addc_co_u32_e64 v238, s[44:45], 0, v238, s[44:45]
	v_cmp_ge_u32_e64 s[54:55], v73, s37
	v_addc_co_u32_e64 v237, s[46:47], 0, v237, s[46:47]
	v_addc_co_u32_e64 v238, s[48:49], 0, v238, s[48:49]
	v_addc_co_u32_e64 v237, s[50:51], 0, v237, s[50:51]
	v_addc_co_u32_e64 v238, s[54:55], 0, v238, s[54:55]
	s_mov_b32 s2, 0
	s_add_i32 s22, s2, s22
	s_andn2_b64 vcc, exec, s[16:17]
	s_cbranch_vccz .LBB0_507

; DEVI int count_ge8(const unsigned* k, unsigned mid) {
;     ...
;     asm("v_cmp_ge_u32_e64 %0, %12, %20\n\t"
;         "v_cmp_ge_u32_e64 %1, %13, %20\n\t"
;         "v_cmp_ge_u32_e64 %2, %14, %20\n\t"
;         "v_cmp_ge_u32_e64 %3, %15, %20\n\t"
;         "v_cmp_ge_u32_e64 %4, %16, %20\n\t"
;         "v_cmp_ge_u32_e64 %5, %17, %20\n\t"
;         "v_cmp_ge_u32_e64 %6, %18, %20\n\t"
;         "v_cmp_ge_u32_e64 %7, %19, %20\n\t"
;         "s_bcnt1_i32_b64 %8, %0\n\t"
;         "s_bcnt1_i32_b64 %9, %1\n\t"
;         "s_bcnt1_i32_b64 %10, %2\n\t"
;         "s_bcnt1_i32_b64 %11, %3\n\t"
;         "s_add_i32 %8, %8, %9\n\t"
;         "s_add_i32 %10, %10, %11\n\t"
;         "s_bcnt1_i32_b64 %9, %4\n\t"
;         "s_bcnt1_i32_b64 %11, %5\n\t"
;         "s_add_i32 %8, %8, %10\n\t"
;         "s_add_i32 %9, %9, %11\n\t"
;         "s_bcnt1_i32_b64 %10, %6\n\t"
;         "s_bcnt1_i32_b64 %11, %7\n\t"
;         "s_add_i32 %8, %8, %9\n\t"
;         "s_add_i32 %10, %10, %11\n\t"
;         "s_add_i32 %8, %8, %10"
; DEVI void topk_select2(const unsigned (&kA)[64], const unsigned (&kB)[64], const bool two, const int ng, const int lim, bf16_t* mrowA, bf16_t* mrowB, const int lane) {
;     ...
;             cB = count_ge8(&kB[0], midB);
;             if (ng > 1) cB += count_ge8(&kB[8], midB);
;             if (ng > 2) cB += count_ge8(&kB[16], midB);
;             if (ng > 3) cB += count_ge8(&kB[24], midB);
;             if (ng > 4) cB += count_ge8(&kB[32], midB);
;             if (ng > 5) cB += count_ge8(&kB[40], midB);
;             if (ng > 6) cB += count_ge8(&kB[48], midB);
;             if (ng > 7) cB += count_ge8(&kB[56], midB);
.LBB0_525:
	v_cmp_ge_u32_e64 s[4:5], v66, s37
	v_cmp_ge_u32_e64 s[40:41], v67, s37
	v_cmp_ge_u32_e64 s[42:43], v26, s37
	v_cmp_ge_u32_e64 s[44:45], v27, s37
	v_addc_co_u32_e64 v237, s[4:5], 0, v237, s[4:5]
	v_cmp_ge_u32_e64 s[46:47], v28, s37
	v_addc_co_u32_e64 v238, s[40:41], 0, v238, s[40:41]
	v_cmp_ge_u32_e64 s[48:49], v29, s37
	v_addc_co_u32_e64 v237, s[42:43], 0, v237, s[42:43]
	v_cmp_ge_u32_e64 s[50:51], v22, s37
	v_addc_co_u32_e64 v238, s[44:45], 0, v238, s[44:45]
	v_cmp_ge_u32_e64 s[54:55], v23, s37
	v_addc_co_u32_e64 v237, s[46:47], 0, v237, s[46:47]
	v_addc_co_u32_e64 v238, s[48:49], 0, v238, s[48:49]
	v_addc_co_u32_e64 v237, s[50:51], 0, v237, s[50:51]
	v_addc_co_u32_e64 v238, s[54:55], 0, v238, s[54:55]
	s_mov_b32 s2, 0
	s_add_i32 s22, s2, s22
	s_andn2_b64 vcc, exec, s[20:21]
	s_cbranch_vccz .LBB0_509
	s_branch .LBB0_510

; DEVI float shx(float v, int m) { return __shfl_xor(v, m); }
; DEVI f32x4 mfma16(bf16x8 a, bf16x8 b, f32x4 c) { return __builtin_amdgcn_mfma_f32_16x16x32_bf16(a, b, c, 0, 0, 0); }
; template <int MODE, bool SAMPLE>
; DEVI void attn_unit(const Params& p, const int b, const int h, const int qt, unsigned char* smem) {
;     ...
;             f32x4 S[4][2];
; #pragma unroll
;             for (int st = 0; st < 4; ++st) {
;                 const bf16x8 k0 = *(const bf16x8*)(Ks + (16 * st + l15) * 144 + (8 * g) * 2);
;                 const bf16x8 k1 = *(const bf16x8*)(Ks + (16 * st + l15) * 144 + (32 + 8 * g) * 2);
; #pragma unroll
;                 for (int j = 0; j < 2; ++j) {
;                     f32x4 d = mfma16(k0, qf[j][0], (f32x4){0.f, 0.f, 0.f, 0.f});
;                     S[st][j] = mfma16(k1, qf[j][1], d);
;                 }
;             }
;             u32x4 pf[2][2];
;             if (MODE == 0) {
;                 float mnew[2], alpha[2];
; #pragma unroll
;                 for (int j = 0; j < 2; ++j) {
;                     float mx = -1e30f;
; #pragma unroll
;                     for (int st = 0; st < 4; ++st) {
;                         const unsigned word = (st < 2) ? mw[j].x : mw[j].y;
;                         const unsigned nib = word >> (16 * (st & 1) + 4 * g);
; #pragma unroll
;                         for (int r = 0; r < 4; ++r) {
;                             const int sel = __builtin_amdgcn_sbfe(nib, r, 1);
;                             const unsigned bits = (__float_as_uint(S[st][j][r]) & (unsigned)sel) | (0xF149F2CAu & ~(unsigned)sel);
;                             S[st][j][r] = __uint_as_float(bits);
;                         }
;                         mx = fmaxf(mx, fmaxf(fmaxf(S[st][j][0], S[st][j][1]), fmaxf(S[st][j][2], S[st][j][3])));
;                     }
;                     mx = fmaxf(mx, shx(mx, 16)); mx = fmaxf(mx, shx(mx, 32));
;                     mnew[j] = (mx > st_m[j] + 8.0f) ? mx : st_m[j];
;                     alpha[j] = __builtin_amdgcn_exp2f(st_m[j] - mnew[j]);
;                 }
.LBB0_909:
	s_or_b64 exec, exec, s[6:7]
	v_cmp_lt_i32_e64 s[0:1], s30, v108
	s_and_saveexec_b64 s[30:31], s[0:1]
	s_cbranch_execz .LBB0_913
	s_bitcmp1_b32 s63, 0
	s_cselect_b32 s0, 0x4600, 0
	s_add_i32 s65, s0, 0
	v_add3_u32 v64, s65, v72, v105
	ds_read_b128 v[110:113], v64
	ds_read_b128 v[114:117], v64 offset:64
	ds_read_b128 v[122:125], v64 offset:2304
	ds_read_b128 v[126:129], v64 offset:2368
	s_nop 0
	s_waitcnt lgkmcnt(3)
	v_mfma_f32_16x16x32_bf16 v[118:121], v[110:113], v[36:39], 0
	v_mfma_f32_16x16x32_bf16 v[110:113], v[110:113], v[44:47], 0
	s_waitcnt lgkmcnt(2)
	v_mfma_f32_16x16x32_bf16 v[118:121], v[114:117], v[32:35], v[118:121]
	v_mfma_f32_16x16x32_bf16 v[132:135], v[114:117], v[40:43], v[110:113]
	s_nop 4
	ds_read_b128 v[112:115], v64 offset:4608
	ds_read_b128 v[136:139], v64 offset:4672
	ds_read_b128 v[140:143], v64 offset:6912
	ds_read_b128 v[144:147], v64 offset:6976
	s_waitcnt lgkmcnt(5)
	v_mfma_f32_16x16x32_bf16 v[148:151], v[122:125], v[36:39], 0
	v_lshrrev_b32_e32 v110, v73, v90
	v_mfma_f32_16x16x32_bf16 v[122:125], v[122:125], v[44:47], 0
	v_bfe_i32 v67, v110, 1, 1
	v_bfe_i32 v64, v110, 0, 1
	v_bitop3_b32 v64, v118, s50, v64 bitop3:0xe4
	v_bitop3_b32 v67, v119, s50, v67 bitop3:0xe4
	s_waitcnt lgkmcnt(3)
	v_mfma_f32_16x16x32_bf16 v[116:119], v[112:115], v[36:39], 0
	v_bfe_i32 v109, v110, 2, 1
	v_bfe_i32 v110, v110, 3, 1
	v_bitop3_b32 v109, v120, s50, v109 bitop3:0xe4
	v_mfma_f32_16x16x32_bf16 v[112:115], v[112:115], v[44:47], 0
	v_bitop3_b32 v110, v121, s50, v110 bitop3:0xe4
	v_mfma_f32_16x16x32_bf16 v[148:151], v[126:129], v[32:35], v[148:151]
	v_max_f32_e32 v111, v109, v110
	v_max3_f32 v158, v64, v67, v111
	v_mfma_f32_16x16x32_bf16 v[124:127], v[126:129], v[40:43], v[122:125]
	v_lshrrev_b32_e32 v128, v102, v90
	v_bfe_i32 v90, v128, 0, 1
	v_bfe_i32 v111, v128, 1, 1
	s_waitcnt lgkmcnt(2)
	v_mfma_f32_16x16x32_bf16 v[152:155], v[136:139], v[40:43], v[112:115]
	v_bitop3_b32 v90, v148, s50, v90 bitop3:0xe4
	v_bitop3_b32 v111, v149, s50, v111 bitop3:0xe4
	s_nop 0
	v_bfe_i32 v112, v128, 2, 1
	v_bfe_i32 v113, v128, 3, 1
	s_waitcnt lgkmcnt(1)
	v_mfma_f32_16x16x32_bf16 v[128:131], v[140:143], v[44:47], 0
	v_bitop3_b32 v112, v150, s50, v112 bitop3:0xe4
	v_bitop3_b32 v113, v151, s50, v113 bitop3:0xe4
	v_mfma_f32_16x16x32_bf16 v[116:119], v[136:139], v[32:35], v[116:119]
	v_max_f32_e32 v114, v112, v113
	v_max3_f32 v114, v90, v111, v114
	v_mfma_f32_16x16x32_bf16 v[120:123], v[140:143], v[36:39], 0
	s_waitcnt lgkmcnt(0)
	v_mfma_f32_16x16x32_bf16 v[138:141], v[144:147], v[40:43], v[128:131]
	s_nop 2
	v_lshrrev_b32_e32 v129, v73, v91
	v_max3_f32 v128, v158, s50, v114
	v_bfe_i32 v114, v129, 0, 1
	v_bfe_i32 v115, v129, 1, 1
	v_mfma_f32_16x16x32_bf16 v[120:123], v[144:147], v[32:35], v[120:123]
	v_bitop3_b32 v114, v116, s50, v114 bitop3:0xe4
	v_bitop3_b32 v115, v117, s50, v115 bitop3:0xe4
	v_bfe_i32 v116, v129, 2, 1
	v_bfe_i32 v117, v129, 3, 1
	v_bitop3_b32 v116, v118, s50, v116 bitop3:0xe4
	v_bitop3_b32 v117, v119, s50, v117 bitop3:0xe4
	v_lshrrev_b32_e32 v91, v102, v91
	v_max_f32_e32 v118, v116, v117
	v_bfe_i32 v119, v91, 0, 1
	v_bitop3_b32 v119, v120, s50, v119 bitop3:0xe4
	v_bfe_i32 v120, v91, 1, 1
	v_bitop3_b32 v120, v121, s50, v120 bitop3:0xe4
	v_bfe_i32 v121, v91, 2, 1
	v_bfe_i32 v91, v91, 3, 1
	v_bitop3_b32 v121, v122, s50, v121 bitop3:0xe4
	v_bitop3_b32 v122, v123, s50, v91 bitop3:0xe4
	v_max_f32_e32 v91, v121, v122
	v_max3_f32 v118, v114, v115, v118
	v_max3_f32 v91, v119, v120, v91
	v_max3_f32 v137, v128, v118, v91
	v_lshrrev_b32_e32 v91, v73, v88
	v_bfe_i32 v118, v91, 0, 1
	v_bitop3_b32 v131, v132, s50, v118 bitop3:0xe4
	v_bfe_i32 v118, v91, 1, 1
	v_bitop3_b32 v132, v133, s50, v118 bitop3:0xe4
	v_bfe_i32 v118, v91, 2, 1
	v_bfe_i32 v91, v91, 3, 1
	v_bitop3_b32 v133, v134, s50, v118 bitop3:0xe4
	v_bitop3_b32 v134, v135, s50, v91 bitop3:0xe4
	v_max_f32_e32 v91, v133, v134
	v_lshrrev_b32_e32 v88, v102, v88
	v_max3_f32 v123, v131, v132, v91
	v_bfe_i32 v91, v88, 0, 1
	v_bitop3_b32 v135, v124, s50, v91 bitop3:0xe4
	v_bfe_i32 v91, v88, 1, 1
	v_bitop3_b32 v136, v125, s50, v91 bitop3:0xe4
	v_bfe_i32 v91, v88, 2, 1
	v_bfe_i32 v88, v88, 3, 1
	v_bitop3_b32 v91, v126, s50, v91 bitop3:0xe4
	v_bitop3_b32 v118, v127, s50, v88 bitop3:0xe4
	v_max_f32_e32 v88, v91, v118
	v_max3_f32 v88, v135, v136, v88
	v_lshrrev_b32_e32 v126, v73, v89
	v_max3_f32 v88, v123, s50, v88
	v_bfe_i32 v123, v126, 0, 1
	v_bfe_i32 v124, v126, 1, 1
	v_bfe_i32 v125, v126, 2, 1
	v_bfe_i32 v126, v126, 3, 1
	v_bitop3_b32 v125, v154, s50, v125 bitop3:0xe4
	v_bitop3_b32 v126, v155, s50, v126 bitop3:0xe4
	v_bitop3_b32 v123, v152, s50, v123 bitop3:0xe4
	v_bitop3_b32 v124, v153, s50, v124 bitop3:0xe4
	v_max_f32_e32 v127, v125, v126
	v_lshrrev_b32_e32 v89, v102, v89
	v_max3_f32 v143, v123, v124, v127
	v_bfe_i32 v127, v89, 0, 1
	v_bfe_i32 v128, v89, 1, 1
	v_bfe_i32 v129, v89, 2, 1
	v_bfe_i32 v89, v89, 3, 1
	v_bitop3_b32 v129, v140, s50, v129 bitop3:0xe4
	v_bitop3_b32 v130, v141, s50, v89 bitop3:0xe4
	v_bitop3_b32 v127, v138, s50, v127 bitop3:0xe4
	v_bitop3_b32 v128, v139, s50, v128 bitop3:0xe4
	v_max_f32_e32 v89, v129, v130
	v_max3_f32 v89, v127, v128, v89
	v_max3_f32 v88, v88, v143, v89
	v_mov_b32_e32 v142, v137
	v_mov_b32_e32 v89, v88
	s_nop 0
	v_permlane16_swap_b32_e32 v142, v137
	v_permlane16_swap_b32_e32 v89, v88
	v_max_f32_e32 v137, v137, v142
	v_max_f32_e32 v88, v88, v89
	v_mov_b32_e32 v142, v137
	v_mov_b32_e32 v89, v88
	s_nop 0
	v_permlane32_swap_b32_e32 v142, v137
	v_permlane32_swap_b32_e32 v89, v88
	v_max_f32_e32 v137, v137, v142
	v_max_f32_e32 v138, v88, v89
	v_pk_add_f32 v[88:89], v[86:87], s[20:21] op_sel_hi:[1,0]
	s_nop 0
	v_cmp_gt_f32_e64 s[0:1], v138, v89
	s_nop 1
	v_cndmask_b32_e64 v89, v87, v138, s[0:1]
	v_cmp_gt_f32_e64 s[0:1], v137, v88
	s_nop 1
	v_cndmask_b32_e64 v88, v86, v137, s[0:1]
	v_pk_add_f32 v[86:87], v[86:87], v[88:89] neg_lo:[0,1] neg_hi:[0,1]
	s_nop 0
	v_exp_f32_e32 v86, v86
	v_exp_f32_e32 v87, v87
	v_cmp_eq_f32_e64 s[0:1], 1.0, v86
	v_cmp_eq_f32_e64 s[6:7], 1.0, v87
	s_and_b64 s[0:1], s[0:1], s[6:7]
	v_cndmask_b32_e64 v137, 0, 1, s[0:1]
	v_cmp_ne_u32_e64 s[0:1], 0, v137
	s_cmp_eq_u64 s[0:1], exec
	s_cbranch_scc1 .LBB0_912
; template <int MODE, bool SAMPLE>
; DEVI void attn_unit(const Params& p, const int b, const int h, const int qt, unsigned char* smem) {
;     ...
;                 if (!__all(alpha[0] == 1.0f && alpha[1] == 1.0f)) {
; #pragma unroll
;                     for (int j = 0; j < 2; ++j)
; #pragma unroll
;                         for (int dt = 0; dt < 4; ++dt) O[dt][j] = O[dt][j] * alpha[j];
;                 }
	v_mov_b32_e32 v138, v87
	v_pk_mul_f32 v[30:31], v[30:31], v[86:87] op_sel_hi:[1,0]
	v_pk_mul_f32 v[28:29], v[28:29], v[86:87] op_sel_hi:[1,0]
	v_pk_mul_f32 v[14:15], v[14:15], v[86:87] op_sel_hi:[1,0]
	v_pk_mul_f32 v[12:13], v[12:13], v[86:87] op_sel_hi:[1,0]
	v_pk_mul_f32 v[26:27], v[26:27], v[86:87] op_sel_hi:[1,0]
	v_pk_mul_f32 v[24:25], v[24:25], v[86:87] op_sel_hi:[1,0]
	v_pk_mul_f32 v[18:19], v[18:19], v[86:87] op_sel_hi:[1,0]
	v_pk_mul_f32 v[16:17], v[16:17], v[86:87] op_sel_hi:[1,0]
	v_pk_mul_f32 v[22:23], v[22:23], v[138:139] op_sel_hi:[1,0]
	v_pk_mul_f32 v[20:21], v[20:21], v[138:139] op_sel_hi:[1,0]
	v_pk_mul_f32 v[6:7], v[6:7], v[138:139] op_sel_hi:[1,0]
	v_pk_mul_f32 v[4:5], v[4:5], v[138:139] op_sel_hi:[1,0]
	v_pk_mul_f32 v[10:11], v[10:11], v[138:139] op_sel_hi:[1,0]
	v_pk_mul_f32 v[8:9], v[8:9], v[138:139] op_sel_hi:[1,0]
	v_pk_mul_f32 v[2:3], v[2:3], v[138:139] op_sel_hi:[1,0]
	v_pk_mul_f32 v[0:1], v[0:1], v[138:139] op_sel_hi:[1,0]

; DEVI float shx(float v, int m) { return __shfl_xor(v, m); }
; DEVI f32x4 mfma16(bf16x8 a, bf16x8 b, f32x4 c) { return __builtin_amdgcn_mfma_f32_16x16x32_bf16(a, b, c, 0, 0, 0); }
; template <int MODE, bool SAMPLE>
; DEVI void attn_unit(const Params& p, const int b, const int h, const int qt, unsigned char* smem) {
;     ...
;             f32x4 S[4][2];
; #pragma unroll
;             for (int st = 0; st < 4; ++st) {
;                 const bf16x8 k0 = *(const bf16x8*)(Ks + (16 * st + l15) * 144 + (8 * g) * 2);
;                 const bf16x8 k1 = *(const bf16x8*)(Ks + (16 * st + l15) * 144 + (32 + 8 * g) * 2);
; #pragma unroll
;                 for (int j = 0; j < 2; ++j) {
;                     f32x4 d = mfma16(k0, qf[j][0], (f32x4){0.f, 0.f, 0.f, 0.f});
;                     S[st][j] = mfma16(k1, qf[j][1], d);
;                 }
;             }
;             u32x4 pf[2][2];
;             if (MODE == 0) {
;                 float mnew[2], alpha[2];
; #pragma unroll
;                 for (int j = 0; j < 2; ++j) {
;                     float mx = -1e30f;
; #pragma unroll
;                     for (int st = 0; st < 4; ++st) {
;                         const unsigned word = (st < 2) ? mw[j].x : mw[j].y;
;                         const unsigned nib = word >> (16 * (st & 1) + 4 * g);
; #pragma unroll
;                         for (int r = 0; r < 4; ++r) {
;                             const int sel = __builtin_amdgcn_sbfe(nib, r, 1);
;                             const unsigned bits = (__float_as_uint(S[st][j][r]) & (unsigned)sel) | (0xF149F2CAu & ~(unsigned)sel);
;                             S[st][j][r] = __uint_as_float(bits);
;                         }
;                         mx = fmaxf(mx, fmaxf(fmaxf(S[st][j][0], S[st][j][1]), fmaxf(S[st][j][2], S[st][j][3])));
;                     }
;                     mx = fmaxf(mx, shx(mx, 16)); mx = fmaxf(mx, shx(mx, 32));
;                     mnew[j] = (mx > st_m[j] + 8.0f) ? mx : st_m[j];
;                     alpha[j] = __builtin_amdgcn_exp2f(st_m[j] - mnew[j]);
;                 }
.LBB0_915:
	s_or_b64 exec, exec, s[0:1]
	v_lshl_add_u64 v[80:81], v[80:81], 0, 8
	v_lshl_add_u64 v[82:83], v[82:83], 0, 8
	s_cmp_eq_u32 s62, s64
	v_lshl_add_u64 v[84:85], v[84:85], 0, s[22:23]
	s_waitcnt lgkmcnt(0)
	s_barrier
	s_cbranch_scc0 .LBB0_905
	s_and_saveexec_b64 s[0:1], s[4:5]
	s_xor_b64 s[0:1], exec, s[0:1]
	v_mbcnt_hi_u32_b32 v51, -1, v224
	v_and_b32_e32 v32, 64, v51
	v_xor_b32_e32 v49, 16, v51
	v_add_u32_e32 v48, 64, v32
	v_xor_b32_e32 v50, 32, v51
	s_andn2_saveexec_b64 s[4:5], s[0:1]
	s_cbranch_execz .LBB0_892
	v_add3_u32 v48, s6, v72, v105
	ds_read_b128 v[50:53], v48
	ds_read_b128 v[54:57], v48 offset:64
	ds_read_b128 v[82:85], v48 offset:2304
	ds_read_b128 v[88:91], v48 offset:2368
	v_and_b32_e32 v58, 64, v95
	v_xor_b32_e32 v49, 16, v95
	s_waitcnt lgkmcnt(3)
	v_mfma_f32_16x16x32_bf16 v[78:81], v[50:53], v[36:39], 0
	ds_read_b128 v[104:107], v48 offset:4608
	ds_read_b128 v[108:111], v48 offset:4672
	ds_read_b128 v[112:115], v48 offset:6912
	ds_read_b128 v[116:119], v48 offset:6976
	v_add_u32_e32 v48, 64, v58
	v_cmp_lt_i32_e32 vcc, v49, v48
	v_mfma_f32_16x16x32_bf16 v[50:53], v[50:53], v[44:47], 0
	v_lshrrev_b32_e32 v64, v102, v74
	s_waitcnt lgkmcnt(6)
	v_mfma_f32_16x16x32_bf16 v[120:123], v[54:57], v[40:43], v[50:53]
	s_waitcnt lgkmcnt(5)
	v_mfma_f32_16x16x32_bf16 v[50:53], v[82:85], v[36:39], 0
	v_mfma_f32_16x16x32_bf16 v[78:81], v[54:57], v[32:35], v[78:81]
	v_cndmask_b32_e32 v54, v95, v49, vcc
	v_lshlrev_b32_e32 v103, 2, v54
	v_lshrrev_b32_e32 v54, v73, v74
	s_waitcnt lgkmcnt(4)
	v_mfma_f32_16x16x32_bf16 v[56:59], v[88:91], v[32:35], v[50:53]
	v_bfe_i32 v55, v54, 0, 1
	s_nop 1
	v_bfe_i32 v50, v54, 1, 1
	v_bitop3_b32 v52, v79, s50, v50 bitop3:0xe4
	v_bfe_i32 v50, v54, 2, 1
	v_bitop3_b32 v53, v80, s50, v50 bitop3:0xe4
	v_bfe_i32 v50, v54, 3, 1
	v_bitop3_b32 v51, v78, s50, v55 bitop3:0xe4
	v_mfma_f32_16x16x32_bf16 v[82:85], v[82:85], v[44:47], 0
	v_bitop3_b32 v54, v81, s50, v50 bitop3:0xe4
	s_waitcnt lgkmcnt(3)
	v_mfma_f32_16x16x32_bf16 v[78:81], v[104:107], v[36:39], 0
	v_max_f32_e32 v50, v53, v54
	v_bfe_i32 v55, v64, 0, 1
	v_bitop3_b32 v55, v56, s50, v55 bitop3:0xe4
	s_waitcnt lgkmcnt(1)
	v_mfma_f32_16x16x32_bf16 v[36:39], v[112:115], v[36:39], 0
	v_bfe_i32 v56, v64, 1, 1
	v_bitop3_b32 v56, v57, s50, v56 bitop3:0xe4
	v_bfe_i32 v57, v64, 2, 1
	v_mfma_f32_16x16x32_bf16 v[82:85], v[88:91], v[40:43], v[82:85]
	v_bitop3_b32 v57, v58, s50, v57 bitop3:0xe4
	v_bfe_i32 v58, v64, 3, 1
	v_bitop3_b32 v58, v59, s50, v58 bitop3:0xe4
	v_mfma_f32_16x16x32_bf16 v[88:91], v[104:107], v[44:47], 0
	v_max_f32_e32 v59, v57, v58
	s_waitcnt lgkmcnt(0)
	v_mfma_f32_16x16x32_bf16 v[104:107], v[116:119], v[32:35], v[36:39]
	v_max3_f32 v50, v51, v52, v50
	v_max3_f32 v59, v55, v56, v59
	v_mfma_f32_16x16x32_bf16 v[36:39], v[112:115], v[44:47], 0
	v_lshrrev_b32_e32 v47, v73, v71
	v_mfma_f32_16x16x32_bf16 v[78:81], v[108:111], v[32:35], v[78:81]
	v_lshrrev_b32_e32 v33, v73, v75
	v_bfe_i32 v34, v33, 0, 1
	v_bfe_i32 v35, v33, 1, 1
	v_mfma_f32_16x16x32_bf16 v[88:91], v[108:111], v[40:43], v[88:91]
	v_max3_f32 v32, v50, s50, v59
	s_nop 2
	v_bitop3_b32 v34, v78, s50, v34 bitop3:0xe4
	v_bitop3_b32 v35, v79, s50, v35 bitop3:0xe4
	v_mfma_f32_16x16x32_bf16 v[108:111], v[116:119], v[40:43], v[36:39]
	v_lshrrev_b32_e32 v41, v102, v75
	v_bfe_i32 v40, v41, 2, 1
	v_bitop3_b32 v40, v106, s50, v40 bitop3:0xe4
	v_bfe_i32 v36, v33, 2, 1
	v_bfe_i32 v33, v33, 3, 1
	v_bitop3_b32 v36, v80, s50, v36 bitop3:0xe4
	v_bitop3_b32 v37, v81, s50, v33 bitop3:0xe4
	v_max_f32_e32 v33, v36, v37
	v_bfe_i32 v38, v41, 0, 1
	v_bfe_i32 v39, v41, 1, 1
	v_bfe_i32 v41, v41, 3, 1
	v_bitop3_b32 v41, v107, s50, v41 bitop3:0xe4
	v_bitop3_b32 v38, v104, s50, v38 bitop3:0xe4
	v_bitop3_b32 v39, v105, s50, v39 bitop3:0xe4
	v_max_f32_e32 v42, v40, v41
	v_xor_b32_e32 v50, 32, v95
	v_max3_f32 v33, v34, v35, v33
	v_max3_f32 v42, v38, v39, v42
	v_cmp_lt_i32_e32 vcc, v50, v48
	v_max3_f32 v32, v32, v33, v42
	ds_bpermute_b32 v33, v103, v32
	v_cndmask_b32_e32 v42, v95, v50, vcc
	v_lshlrev_b32_e32 v80, 2, v42
	v_lshrrev_b32_e32 v42, v73, v70
	v_bfe_i32 v43, v42, 0, 1
	v_bitop3_b32 v72, v120, s50, v43 bitop3:0xe4
	v_bfe_i32 v43, v42, 1, 1
	v_bitop3_b32 v74, v121, s50, v43 bitop3:0xe4
	v_bfe_i32 v43, v42, 2, 1
	v_bfe_i32 v42, v42, 3, 1
	v_bitop3_b32 v75, v122, s50, v43 bitop3:0xe4
	v_bitop3_b32 v76, v123, s50, v42 bitop3:0xe4
	v_max_f32_e32 v42, v75, v76
	v_lshrrev_b32_e32 v43, v102, v70
	v_max3_f32 v44, v72, v74, v42
	v_bfe_i32 v42, v43, 0, 1
	v_bitop3_b32 v78, v82, s50, v42 bitop3:0xe4
	v_bfe_i32 v42, v43, 1, 1
	v_bitop3_b32 v79, v83, s50, v42 bitop3:0xe4
	v_bfe_i32 v42, v43, 2, 1
	v_bfe_i32 v43, v43, 3, 1
	v_bitop3_b32 v42, v84, s50, v42 bitop3:0xe4
	v_bitop3_b32 v43, v85, s50, v43 bitop3:0xe4
	v_max_f32_e32 v45, v42, v43
	v_max3_f32 v45, v78, v79, v45
	v_max3_f32 v81, v44, s50, v45
	v_bfe_i32 v44, v47, 0, 1
	v_bfe_i32 v45, v47, 1, 1
	v_bfe_i32 v46, v47, 2, 1
	v_bfe_i32 v47, v47, 3, 1
	v_bitop3_b32 v46, v90, s50, v46 bitop3:0xe4
	v_bitop3_b32 v47, v91, s50, v47 bitop3:0xe4
	v_bitop3_b32 v44, v88, s50, v44 bitop3:0xe4
	v_bitop3_b32 v45, v89, s50, v45 bitop3:0xe4
	v_max_f32_e32 v59, v46, v47
	v_lshrrev_b32_e32 v70, v102, v71
	v_max3_f32 v82, v44, v45, v59
	v_bfe_i32 v59, v70, 0, 1
	v_bfe_i32 v64, v70, 1, 1
	v_bfe_i32 v67, v70, 2, 1
	v_bfe_i32 v70, v70, 3, 1
	v_bitop3_b32 v67, v110, s50, v67 bitop3:0xe4
	v_bitop3_b32 v70, v111, s50, v70 bitop3:0xe4
	v_bitop3_b32 v59, v108, s50, v59 bitop3:0xe4
	v_bitop3_b32 v64, v109, s50, v64 bitop3:0xe4
	v_max_f32_e32 v71, v67, v70
	v_max3_f32 v71, v59, v64, v71
	v_max3_f32 v71, v81, v82, v71
	ds_bpermute_b32 v81, v103, v71
	s_waitcnt lgkmcnt(1)
	v_max_f32_e32 v32, v32, v33
	ds_bpermute_b32 v33, v80, v32
	s_waitcnt lgkmcnt(1)
	v_max_f32_e32 v71, v71, v81
	ds_bpermute_b32 v81, v80, v71
	s_waitcnt lgkmcnt(1)
	v_max_f32_e32 v32, v32, v33
	v_add_f32_e32 v33, 0x41000000, v86
	v_cmp_gt_f32_e32 vcc, v32, v33
	s_waitcnt lgkmcnt(0)
	v_max_f32_e32 v33, v71, v81
	v_add_f32_e32 v71, 0x41000000, v87
	v_cndmask_b32_e32 v80, v86, v32, vcc
	v_cmp_gt_f32_e32 vcc, v33, v71
	v_sub_f32_e32 v32, v86, v80
	v_exp_f32_e32 v32, v32
	v_cndmask_b32_e32 v71, v87, v33, vcc
	v_sub_f32_e32 v33, v87, v71
	v_exp_f32_e32 v33, v33
	v_cmp_eq_f32_e32 vcc, 1.0, v32
	v_cmp_eq_f32_e64 s[0:1], 1.0, v33
	s_and_b64 s[0:1], vcc, s[0:1]
	s_nop 0
	v_cndmask_b32_e64 v81, 0, 1, s[0:1]
	v_cmp_ne_u32_e32 vcc, 0, v81
	s_cmp_eq_u64 vcc, exec
	s_cbranch_scc1 .LBB0_891
; template <int MODE, bool SAMPLE>
; DEVI void attn_unit(const Params& p, const int b, const int h, const int qt, unsigned char* smem) {
;     ...
;                 if (!__all(alpha[0] == 1.0f && alpha[1] == 1.0f)) {
; #pragma unroll
;                     for (int j = 0; j < 2; ++j)
; #pragma unroll
;                         for (int dt = 0; dt < 4; ++dt) O[dt][j] = O[dt][j] * alpha[j];
;                 }
	v_mov_b32_e32 v82, v33
	v_pk_mul_f32 v[30:31], v[30:31], v[32:33] op_sel_hi:[1,0]
	v_pk_mul_f32 v[28:29], v[28:29], v[32:33] op_sel_hi:[1,0]
	v_pk_mul_f32 v[14:15], v[14:15], v[32:33] op_sel_hi:[1,0]
	v_pk_mul_f32 v[12:13], v[12:13], v[32:33] op_sel_hi:[1,0]
	v_pk_mul_f32 v[26:27], v[26:27], v[32:33] op_sel_hi:[1,0]
	v_pk_mul_f32 v[24:25], v[24:25], v[32:33] op_sel_hi:[1,0]
	v_pk_mul_f32 v[18:19], v[18:19], v[32:33] op_sel_hi:[1,0]
	v_pk_mul_f32 v[16:17], v[16:17], v[32:33] op_sel_hi:[1,0]
	v_pk_mul_f32 v[22:23], v[22:23], v[82:83] op_sel_hi:[1,0]
	v_pk_mul_f32 v[20:21], v[20:21], v[82:83] op_sel_hi:[1,0]
	v_pk_mul_f32 v[6:7], v[6:7], v[82:83] op_sel_hi:[1,0]
	v_pk_mul_f32 v[4:5], v[4:5], v[82:83] op_sel_hi:[1,0]
	v_pk_mul_f32 v[10:11], v[10:11], v[82:83] op_sel_hi:[1,0]
	v_pk_mul_f32 v[8:9], v[8:9], v[82:83] op_sel_hi:[1,0]
	v_pk_mul_f32 v[2:3], v[2:3], v[82:83] op_sel_hi:[1,0]
	v_pk_mul_f32 v[0:1], v[0:1], v[82:83] op_sel_hi:[1,0]
	s_branch .LBB0_891

; DEVI float shx(float v, int m) { return __shfl_xor(v, m); }
; DEVI f32x4 mfma16(bf16x8 a, bf16x8 b, f32x4 c) { return __builtin_amdgcn_mfma_f32_16x16x32_bf16(a, b, c, 0, 0, 0); }
; template <int MODE, bool SAMPLE>
; DEVI void attn_unit(const Params& p, const int b, const int h, const int qt, unsigned char* smem) {
;     ...
;             f32x4 S[4][2];
; #pragma unroll
;             for (int st = 0; st < 4; ++st) {
;                 const bf16x8 k0 = *(const bf16x8*)(Ks + (16 * st + l15) * 144 + (8 * g) * 2);
;                 const bf16x8 k1 = *(const bf16x8*)(Ks + (16 * st + l15) * 144 + (32 + 8 * g) * 2);
; #pragma unroll
;                 for (int j = 0; j < 2; ++j) {
;                     f32x4 d = mfma16(k0, qf[j][0], (f32x4){0.f, 0.f, 0.f, 0.f});
;                     S[st][j] = mfma16(k1, qf[j][1], d);
;                 }
;             }
;             u32x4 pf[2][2];
;             if (MODE == 0) {
;                 float mnew[2], alpha[2];
; #pragma unroll
;                 for (int j = 0; j < 2; ++j) {
;                     float mx = -1e30f;
; #pragma unroll
;                     for (int st = 0; st < 4; ++st) {
;                         const unsigned word = (st < 2) ? mw[j].x : mw[j].y;
;                         const unsigned nib = word >> (16 * (st & 1) + 4 * g);
; #pragma unroll
;                         for (int r = 0; r < 4; ++r) {
;                             const int sel = __builtin_amdgcn_sbfe(nib, r, 1);
;                             const unsigned bits = (__float_as_uint(S[st][j][r]) & (unsigned)sel) | (0xF149F2CAu & ~(unsigned)sel);
;                             S[st][j][r] = __uint_as_float(bits);
;                         }
;                         mx = fmaxf(mx, fmaxf(fmaxf(S[st][j][0], S[st][j][1]), fmaxf(S[st][j][2], S[st][j][3])));
;                     }
;                     mx = fmaxf(mx, shx(mx, 16)); mx = fmaxf(mx, shx(mx, 32));
;                     mnew[j] = (mx > st_m[j] + 8.0f) ? mx : st_m[j];
;                     alpha[j] = __builtin_amdgcn_exp2f(st_m[j] - mnew[j]);
;                 }
.LBB0_928:
	s_or_b64 exec, exec, s[0:1]
	s_and_saveexec_b64 s[24:25], vcc
	s_cbranch_execz .LBB0_932
	s_bitcmp1_b32 s57, 0
	s_cselect_b32 s0, 0x4600, 0
	s_add_i32 s58, s0, 0
	v_add_u32_e32 v67, s58, v74
	v_add_u32_e32 v85, v67, v109
	ds_read_b128 v[114:117], v85
	ds_read_b128 v[118:121], v85 offset:64
	ds_read_b128 v[126:129], v85 offset:2304
	ds_read_b128 v[130:133], v85 offset:2368
	v_lshrrev_b32_e32 v158, v75, v90
	v_bfe_i32 v159, v158, 0, 1
	s_waitcnt lgkmcnt(3)
	v_mfma_f32_16x16x32_bf16 v[122:125], v[114:117], v[40:43], 0
	v_add_u32_e32 v67, v67, v104
	ds_read_b128 v[138:141], v85 offset:4608
	ds_read_b128 v[142:145], v85 offset:4672
	v_bfe_i32 v85, v158, 1, 1
	v_mfma_f32_16x16x32_bf16 v[114:117], v[114:117], v[44:47], 0
	ds_read_b128 v[150:153], v67
	ds_read_b128 v[154:157], v67 offset:64
	s_waitcnt lgkmcnt(6)
	v_mfma_f32_16x16x32_bf16 v[122:125], v[118:121], v[36:39], v[122:125]
	s_waitcnt lgkmcnt(5)
	v_mfma_f32_16x16x32_bf16 v[134:137], v[126:129], v[40:43], 0
	v_mfma_f32_16x16x32_bf16 v[146:149], v[118:121], v[32:35], v[114:117]
	s_nop 4
	v_bitop3_b32 v67, v122, s50, v159 bitop3:0xe4
	v_bitop3_b32 v85, v123, s50, v85 bitop3:0xe4
	v_mfma_f32_16x16x32_bf16 v[120:123], v[126:129], v[44:47], 0
	v_bfe_i32 v114, v158, 2, 1
	v_bfe_i32 v115, v158, 3, 1
	v_bitop3_b32 v114, v124, s50, v114 bitop3:0xe4
	s_waitcnt lgkmcnt(4)
	v_mfma_f32_16x16x32_bf16 v[116:119], v[130:133], v[36:39], v[134:137]
	v_bitop3_b32 v115, v125, s50, v115 bitop3:0xe4
	v_mfma_f32_16x16x32_bf16 v[128:131], v[130:133], v[32:35], v[120:123]
	v_lshrrev_b32_e32 v132, v103, v90
	v_bfe_i32 v90, v132, 0, 1
	s_nop 3
	v_bitop3_b32 v90, v116, s50, v90 bitop3:0xe4
	v_max_f32_e32 v124, v114, v115
	s_waitcnt lgkmcnt(3)
	v_mfma_f32_16x16x32_bf16 v[120:123], v[138:141], v[40:43], 0
	v_bfe_i32 v116, v132, 1, 1
	v_bitop3_b32 v116, v117, s50, v116 bitop3:0xe4
	v_bfe_i32 v117, v132, 2, 1
	v_max3_f32 v136, v67, v85, v124
	v_mfma_f32_16x16x32_bf16 v[124:127], v[138:141], v[44:47], 0
	v_bitop3_b32 v117, v118, s50, v117 bitop3:0xe4
	v_bfe_i32 v118, v132, 3, 1
	v_bitop3_b32 v118, v119, s50, v118 bitop3:0xe4
	s_waitcnt lgkmcnt(2)
	v_mfma_f32_16x16x32_bf16 v[120:123], v[142:145], v[36:39], v[120:123]
	v_max_f32_e32 v119, v117, v118
	v_mfma_f32_16x16x32_bf16 v[132:135], v[142:145], v[32:35], v[124:127]
	v_max3_f32 v119, v90, v116, v119
	v_lshrrev_b32_e32 v141, v75, v91
	v_max3_f32 v140, v136, s50, v119
	s_waitcnt lgkmcnt(1)
	v_mfma_f32_16x16x32_bf16 v[124:127], v[150:153], v[40:43], 0
	v_bfe_i32 v119, v141, 0, 1
	v_bitop3_b32 v119, v120, s50, v119 bitop3:0xe4
	v_bfe_i32 v120, v141, 1, 1
	v_mfma_f32_16x16x32_bf16 v[136:139], v[150:153], v[44:47], 0
	v_bitop3_b32 v120, v121, s50, v120 bitop3:0xe4
	v_bfe_i32 v121, v141, 2, 1
	v_bitop3_b32 v121, v122, s50, v121 bitop3:0xe4
	s_waitcnt lgkmcnt(0)
	v_mfma_f32_16x16x32_bf16 v[124:127], v[154:157], v[36:39], v[124:127]
	v_bfe_i32 v122, v141, 3, 1
	v_bitop3_b32 v122, v123, s50, v122 bitop3:0xe4
	v_mfma_f32_16x16x32_bf16 v[142:145], v[154:157], v[32:35], v[136:139]
	v_lshrrev_b32_e32 v91, v103, v91
	s_nop 1
	v_max_f32_e32 v123, v121, v122
	v_bfe_i32 v136, v91, 0, 1
	v_bitop3_b32 v124, v124, s50, v136 bitop3:0xe4
	v_bfe_i32 v136, v91, 1, 1
	v_bitop3_b32 v125, v125, s50, v136 bitop3:0xe4
	v_bfe_i32 v136, v91, 2, 1
	v_bfe_i32 v91, v91, 3, 1
	v_bitop3_b32 v126, v126, s50, v136 bitop3:0xe4
	v_bitop3_b32 v127, v127, s50, v91 bitop3:0xe4
	v_max_f32_e32 v91, v126, v127
	v_max3_f32 v123, v119, v120, v123
	v_max3_f32 v91, v124, v125, v91
	v_max3_f32 v150, v140, v123, v91
	v_lshrrev_b32_e32 v91, v75, v88
	v_bfe_i32 v123, v91, 0, 1
	v_bitop3_b32 v136, v146, s50, v123 bitop3:0xe4
	v_bfe_i32 v123, v91, 1, 1
	v_bitop3_b32 v137, v147, s50, v123 bitop3:0xe4
	v_bfe_i32 v123, v91, 2, 1
	v_bfe_i32 v91, v91, 3, 1
	v_bitop3_b32 v138, v148, s50, v123 bitop3:0xe4
	v_bitop3_b32 v139, v149, s50, v91 bitop3:0xe4
	v_max_f32_e32 v91, v138, v139
	v_lshrrev_b32_e32 v88, v103, v88
	v_max3_f32 v146, v136, v137, v91
	v_bfe_i32 v91, v88, 0, 1
	v_bitop3_b32 v140, v128, s50, v91 bitop3:0xe4
	v_bfe_i32 v91, v88, 1, 1
	v_bitop3_b32 v141, v129, s50, v91 bitop3:0xe4
	v_bfe_i32 v91, v88, 2, 1
	v_bfe_i32 v88, v88, 3, 1
	v_bitop3_b32 v91, v130, s50, v91 bitop3:0xe4
	v_bitop3_b32 v123, v131, s50, v88 bitop3:0xe4
	v_lshrrev_b32_e32 v131, v75, v89
	v_max_f32_e32 v88, v91, v123
	v_bfe_i32 v128, v131, 0, 1
	v_bfe_i32 v129, v131, 1, 1
	v_bfe_i32 v130, v131, 2, 1
	v_bfe_i32 v131, v131, 3, 1
	v_bitop3_b32 v130, v134, s50, v130 bitop3:0xe4
	v_bitop3_b32 v131, v135, s50, v131 bitop3:0xe4
	v_bitop3_b32 v128, v132, s50, v128 bitop3:0xe4
	v_bitop3_b32 v129, v133, s50, v129 bitop3:0xe4
	v_max3_f32 v88, v140, v141, v88
	v_max_f32_e32 v132, v130, v131
	v_lshrrev_b32_e32 v89, v103, v89
	v_max3_f32 v88, v146, s50, v88
	v_max3_f32 v146, v128, v129, v132
	v_bfe_i32 v132, v89, 0, 1
	v_bfe_i32 v133, v89, 1, 1
	v_bfe_i32 v134, v89, 2, 1
	v_bfe_i32 v89, v89, 3, 1
	v_bitop3_b32 v134, v144, s50, v134 bitop3:0xe4
	v_bitop3_b32 v135, v145, s50, v89 bitop3:0xe4
	v_bitop3_b32 v132, v142, s50, v132 bitop3:0xe4
	v_bitop3_b32 v133, v143, s50, v133 bitop3:0xe4
	v_max_f32_e32 v89, v134, v135
	v_max3_f32 v89, v132, v133, v89
	v_max3_f32 v88, v88, v146, v89
	v_mov_b32_e32 v151, v150
	v_mov_b32_e32 v89, v88
	s_nop 0
	v_permlane16_swap_b32_e32 v151, v150
	v_permlane16_swap_b32_e32 v89, v88
	v_max_f32_e32 v142, v150, v151
	v_max_f32_e32 v88, v88, v89
	v_mov_b32_e32 v151, v142
	v_mov_b32_e32 v89, v88
	s_nop 0
	v_permlane32_swap_b32_e32 v151, v142
	v_permlane32_swap_b32_e32 v89, v88
	v_max_f32_e32 v142, v142, v151
	v_max_f32_e32 v143, v88, v89
	v_pk_add_f32 v[88:89], v[86:87], s[20:21] op_sel_hi:[1,0]
	s_nop 0
	v_cmp_gt_f32_e64 s[0:1], v143, v89
	s_nop 1
	v_cndmask_b32_e64 v89, v87, v143, s[0:1]
	v_cmp_gt_f32_e64 s[0:1], v142, v88
	s_nop 1
	v_cndmask_b32_e64 v88, v86, v142, s[0:1]
	v_pk_add_f32 v[86:87], v[86:87], v[88:89] neg_lo:[0,1] neg_hi:[0,1]
	s_nop 0
	v_exp_f32_e32 v86, v86
	v_exp_f32_e32 v87, v87
	v_cmp_eq_f32_e64 s[0:1], 1.0, v86
	v_cmp_eq_f32_e64 s[10:11], 1.0, v87
	s_and_b64 s[0:1], s[0:1], s[10:11]
	v_cndmask_b32_e64 v142, 0, 1, s[0:1]
	v_cmp_ne_u32_e64 s[0:1], 0, v142
	s_cmp_eq_u64 s[0:1], exec
	s_cbranch_scc1 .LBB0_931
; template <int MODE, bool SAMPLE>
; DEVI void attn_unit(const Params& p, const int b, const int h, const int qt, unsigned char* smem) {
;     ...
;                 if (!__all(alpha[0] == 1.0f && alpha[1] == 1.0f)) {
; #pragma unroll
;                     for (int j = 0; j < 2; ++j)
; #pragma unroll
;                         for (int dt = 0; dt < 4; ++dt) O[dt][j] = O[dt][j] * alpha[j];
;                 }
	v_mov_b32_e32 v142, v87
	v_pk_mul_f32 v[30:31], v[30:31], v[86:87] op_sel_hi:[1,0]
	v_pk_mul_f32 v[28:29], v[28:29], v[86:87] op_sel_hi:[1,0]
	v_pk_mul_f32 v[18:19], v[18:19], v[86:87] op_sel_hi:[1,0]
	v_pk_mul_f32 v[16:17], v[16:17], v[86:87] op_sel_hi:[1,0]
	v_pk_mul_f32 v[26:27], v[26:27], v[86:87] op_sel_hi:[1,0]
	v_pk_mul_f32 v[24:25], v[24:25], v[86:87] op_sel_hi:[1,0]
	v_pk_mul_f32 v[22:23], v[22:23], v[86:87] op_sel_hi:[1,0]
	v_pk_mul_f32 v[20:21], v[20:21], v[86:87] op_sel_hi:[1,0]
	v_pk_mul_f32 v[14:15], v[14:15], v[142:143] op_sel_hi:[1,0]
	v_pk_mul_f32 v[12:13], v[12:13], v[142:143] op_sel_hi:[1,0]
	v_pk_mul_f32 v[6:7], v[6:7], v[142:143] op_sel_hi:[1,0]
	v_pk_mul_f32 v[4:5], v[4:5], v[142:143] op_sel_hi:[1,0]
	v_pk_mul_f32 v[10:11], v[10:11], v[142:143] op_sel_hi:[1,0]
	v_pk_mul_f32 v[8:9], v[8:9], v[142:143] op_sel_hi:[1,0]
	v_pk_mul_f32 v[2:3], v[2:3], v[142:143] op_sel_hi:[1,0]
	v_pk_mul_f32 v[0:1], v[0:1], v[142:143] op_sel_hi:[1,0]

; DEVI float shx(float v, int m) { return __shfl_xor(v, m); }
; template <int MODE, bool SAMPLE>
; DEVI void attn_unit(const Params& p, const int b, const int h, const int qt, unsigned char* smem) {
;     ...
;             f32x4 S[4][2];
; #pragma unroll
;             for (int st = 0; st < 4; ++st) {
;                 const bf16x8 k0 = *(const bf16x8*)(Ks + (16 * st + l15) * 144 + (8 * g) * 2);
;                 const bf16x8 k1 = *(const bf16x8*)(Ks + (16 * st + l15) * 144 + (32 + 8 * g) * 2);
; #pragma unroll
;                 for (int j = 0; j < 2; ++j) {
;                     f32x4 d = mfma16(k0, qf[j][0], (f32x4){0.f, 0.f, 0.f, 0.f});
;                     S[st][j] = mfma16(k1, qf[j][1], d);
;                 }
;             }
;             u32x4 pf[2][2];
;             if (MODE == 0) {
;                 float mnew[2], alpha[2];
; #pragma unroll
;                 for (int j = 0; j < 2; ++j) {
;                     float mx = -1e30f;
; #pragma unroll
;                     for (int st = 0; st < 4; ++st) {
;                         const unsigned word = (st < 2) ? mw[j].x : mw[j].y;
;                         const unsigned nib = word >> (16 * (st & 1) + 4 * g);
; #pragma unroll
;                         for (int r = 0; r < 4; ++r) {
;                             const int sel = __builtin_amdgcn_sbfe(nib, r, 1);
;                             const unsigned bits = (__float_as_uint(S[st][j][r]) & (unsigned)sel) | (0xF149F2CAu & ~(unsigned)sel);
;                             S[st][j][r] = __uint_as_float(bits);
;                         }
;                         mx = fmaxf(mx, fmaxf(fmaxf(S[st][j][0], S[st][j][1]), fmaxf(S[st][j][2], S[st][j][3])));
;                     }
;                     mx = fmaxf(mx, shx(mx, 16)); mx = fmaxf(mx, shx(mx, 32));
;                     mnew[j] = (mx > st_m[j] + 8.0f) ? mx : st_m[j];
;                     alpha[j] = __builtin_amdgcn_exp2f(st_m[j] - mnew[j]);
;                 }
; #pragma unroll
;                 for (int j = 0; j < 2; ++j) {
;                     float ps = 0.f;
; #pragma unroll
;                     for (int st = 0; st < 4; ++st)
; #pragma unroll
;                         for (int r = 0; r < 4; ++r) { const float pv = __builtin_amdgcn_exp2f(S[st][j][r] - mnew[j]);   S[st][j][r] = pv; ps += pv; }
;                     st_l[j] = st_l[j] * alpha[j] + ps;
;                     st_m[j] = mnew[j];
;                 }
.LBB0_934:
	s_and_saveexec_b64 s[6:7], vcc
	s_cbranch_execz .LBB0_938
	v_add_u32_e32 v60, 0, v74
	v_add_u32_e32 v64, v60, v109
	ds_read_b128 v[48:51], v64
	ds_read_b128 v[52:55], v64 offset:64
	v_add_u32_e32 v74, v60, v104
	ds_read_b128 v[60:63], v64 offset:2304
	ds_read_b128 v[80:83], v64 offset:2368
	s_waitcnt lgkmcnt(3)
	v_mfma_f32_16x16x32_bf16 v[56:59], v[48:51], v[40:43], 0
	v_lshrrev_b32_e32 v67, v75, v78
	v_bfe_i32 v84, v67, 0, 1
	v_bfe_i32 v85, v67, 1, 1
	v_mfma_f32_16x16x32_bf16 v[48:51], v[48:51], v[44:47], 0
	ds_read_b128 v[104:107], v64 offset:4608
	ds_read_b128 v[108:111], v64 offset:4672
	ds_read_b128 v[112:115], v74
	ds_read_b128 v[116:119], v74 offset:64
	s_waitcnt lgkmcnt(6)
	v_mfma_f32_16x16x32_bf16 v[56:59], v[52:55], v[36:39], v[56:59]
	v_mfma_f32_16x16x32_bf16 v[88:91], v[52:55], v[32:35], v[48:51]
	s_waitcnt lgkmcnt(5)
	v_mfma_f32_16x16x32_bf16 v[50:53], v[60:63], v[40:43], 0
	s_nop 4
	v_bitop3_b32 v49, v56, s50, v84 bitop3:0xe4
	v_bfe_i32 v56, v67, 2, 1
	v_bitop3_b32 v48, v57, s50, v85 bitop3:0xe4
	s_waitcnt lgkmcnt(4)
	v_mfma_f32_16x16x32_bf16 v[52:55], v[80:83], v[36:39], v[50:53]
	s_nop 2
	v_bfe_i32 v51, v67, 3, 1
	v_bitop3_b32 v50, v58, s50, v56 bitop3:0xe4
	v_bitop3_b32 v51, v59, s50, v51 bitop3:0xe4
	v_mfma_f32_16x16x32_bf16 v[56:59], v[60:63], v[44:47], 0
	v_max_f32_e32 v60, v50, v51
	v_max3_f32 v64, v49, v48, v60
	s_waitcnt lgkmcnt(3)
	v_mfma_f32_16x16x32_bf16 v[60:63], v[104:107], v[40:43], 0
	v_lshrrev_b32_e32 v67, v103, v78
	v_bfe_i32 v74, v67, 0, 1
	v_bitop3_b32 v52, v52, s50, v74 bitop3:0xe4
	v_mfma_f32_16x16x32_bf16 v[56:59], v[80:83], v[32:35], v[56:59]
	v_bfe_i32 v74, v67, 1, 1
	v_bitop3_b32 v53, v53, s50, v74 bitop3:0xe4
	v_bfe_i32 v74, v67, 2, 1
	v_mfma_f32_16x16x32_bf16 v[80:83], v[104:107], v[44:47], 0
	v_bfe_i32 v67, v67, 3, 1
	v_bitop3_b32 v54, v54, s50, v74 bitop3:0xe4
	v_bitop3_b32 v55, v55, s50, v67 bitop3:0xe4
	s_waitcnt lgkmcnt(1)
	v_mfma_f32_16x16x32_bf16 v[104:107], v[112:115], v[40:43], 0
	v_lshrrev_b32_e32 v41, v75, v79
	v_bfe_i32 v40, v41, 0, 1
	v_lshrrev_b32_e32 v43, v103, v79
	v_mfma_f32_16x16x32_bf16 v[60:63], v[108:111], v[36:39], v[60:63]
	v_bfe_i32 v42, v43, 2, 1
	s_nop 0
	s_nop 0
	s_waitcnt lgkmcnt(0)
	v_mfma_f32_16x16x32_bf16 v[104:107], v[116:119], v[36:39], v[104:107]
	v_bfe_i32 v37, v41, 2, 1
	v_bfe_i32 v38, v41, 3, 1
	s_nop 0
	v_bitop3_b32 v37, v62, s50, v37 bitop3:0xe4
	v_bitop3_b32 v38, v63, s50, v38 bitop3:0xe4
	v_bfe_i32 v36, v41, 1, 1
	v_bitop3_b32 v40, v60, s50, v40 bitop3:0xe4
	v_bitop3_b32 v36, v61, s50, v36 bitop3:0xe4
	v_max_f32_e32 v39, v37, v38
	v_max3_f32 v60, v40, v36, v39
	v_bfe_i32 v39, v43, 0, 1
	v_bfe_i32 v41, v43, 1, 1
	v_bfe_i32 v43, v43, 3, 1
	v_bitop3_b32 v42, v106, s50, v42 bitop3:0xe4
	v_bitop3_b32 v43, v107, s50, v43 bitop3:0xe4
	v_max_f32_e32 v67, v54, v55
	v_max3_f32 v67, v52, v53, v67
	v_bitop3_b32 v39, v104, s50, v39 bitop3:0xe4
	v_bitop3_b32 v41, v105, s50, v41 bitop3:0xe4
	v_max_f32_e32 v61, v42, v43
	v_max3_f32 v64, v64, s50, v67
	v_max3_f32 v61, v39, v41, v61
	v_max3_f32 v60, v64, v60, v61
	v_mfma_f32_16x16x32_bf16 v[44:47], v[112:115], v[44:47], 0
	ds_bpermute_b32 v61, v98, v60
	v_mfma_f32_16x16x32_bf16 v[80:83], v[108:111], v[32:35], v[80:83]
	v_mfma_f32_16x16x32_bf16 v[104:107], v[116:119], v[32:35], v[44:47]
	v_lshrrev_b32_e32 v34, v75, v76
	s_waitcnt lgkmcnt(0)
	v_bfe_i32 v35, v34, 0, 1
	v_max_f32_e32 v32, v60, v61
	v_bitop3_b32 v60, v88, s50, v35 bitop3:0xe4
	v_bfe_i32 v35, v34, 1, 1
	v_bitop3_b32 v61, v89, s50, v35 bitop3:0xe4
	v_bfe_i32 v35, v34, 2, 1
	v_bfe_i32 v34, v34, 3, 1
	v_bitop3_b32 v62, v90, s50, v35 bitop3:0xe4
	v_bitop3_b32 v63, v91, s50, v34 bitop3:0xe4
	v_max_f32_e32 v34, v62, v63
	v_lshrrev_b32_e32 v35, v103, v76
	v_max3_f32 v44, v60, v61, v34
	v_bfe_i32 v34, v35, 0, 1
	v_bitop3_b32 v64, v56, s50, v34 bitop3:0xe4
	v_bfe_i32 v34, v35, 1, 1
	v_bitop3_b32 v67, v57, s50, v34 bitop3:0xe4
	v_bfe_i32 v34, v35, 2, 1
	v_bfe_i32 v35, v35, 3, 1
	v_bitop3_b32 v34, v58, s50, v34 bitop3:0xe4
	v_bitop3_b32 v35, v59, s50, v35 bitop3:0xe4
	v_max_f32_e32 v45, v34, v35
	v_max3_f32 v45, v64, v67, v45
	v_lshrrev_b32_e32 v47, v75, v77
	v_max3_f32 v74, v44, s50, v45
	v_bfe_i32 v44, v47, 0, 1
	v_bfe_i32 v45, v47, 1, 1
	v_bfe_i32 v46, v47, 2, 1
	v_bfe_i32 v47, v47, 3, 1
	v_bitop3_b32 v46, v82, s50, v46 bitop3:0xe4
	v_bitop3_b32 v47, v83, s50, v47 bitop3:0xe4
	v_bitop3_b32 v44, v80, s50, v44 bitop3:0xe4
	v_bitop3_b32 v45, v81, s50, v45 bitop3:0xe4
	v_max_f32_e32 v56, v46, v47
	v_lshrrev_b32_e32 v59, v103, v77
	v_max3_f32 v76, v44, v45, v56
	v_bfe_i32 v56, v59, 0, 1
	v_bfe_i32 v57, v59, 1, 1
	v_bfe_i32 v58, v59, 2, 1
	v_bfe_i32 v59, v59, 3, 1
	v_bitop3_b32 v58, v106, s50, v58 bitop3:0xe4
	v_bitop3_b32 v59, v107, s50, v59 bitop3:0xe4
	v_bitop3_b32 v56, v104, s50, v56 bitop3:0xe4
	v_bitop3_b32 v57, v105, s50, v57 bitop3:0xe4
	v_max_f32_e32 v77, v58, v59
	v_max3_f32 v77, v56, v57, v77
	v_max3_f32 v74, v74, v76, v77
	ds_bpermute_b32 v76, v98, v74
	ds_bpermute_b32 v33, v99, v32
	s_waitcnt lgkmcnt(1)
	v_max_f32_e32 v74, v74, v76
	ds_bpermute_b32 v77, v99, v74
	s_waitcnt lgkmcnt(1)
	v_max_f32_e32 v32, v32, v33
	v_add_f32_e32 v33, 0x41000000, v86
	v_cmp_gt_f32_e64 s[0:1], v32, v33
	s_waitcnt lgkmcnt(0)
	v_max_f32_e32 v33, v74, v77
	v_add_f32_e32 v74, 0x41000000, v87
	v_cndmask_b32_e64 v76, v86, v32, s[0:1]
	v_cmp_gt_f32_e64 s[0:1], v33, v74
	v_sub_f32_e32 v32, v86, v76
	v_exp_f32_e32 v32, v32
	v_cndmask_b32_e64 v74, v87, v33, s[0:1]
	v_sub_f32_e32 v33, v87, v74
	v_exp_f32_e32 v33, v33
	v_cmp_eq_f32_e64 s[0:1], 1.0, v32
	v_cmp_eq_f32_e64 s[4:5], 1.0, v33
	s_and_b64 s[0:1], s[0:1], s[4:5]
	v_cndmask_b32_e64 v77, 0, 1, s[0:1]
	v_cmp_ne_u32_e64 s[0:1], 0, v77
	s_cmp_eq_u64 s[0:1], exec
	s_cbranch_scc1 .LBB0_937
	v_mov_b32_e32 v78, v33
	v_pk_mul_f32 v[30:31], v[30:31], v[32:33] op_sel_hi:[1,0]
	v_pk_mul_f32 v[28:29], v[28:29], v[32:33] op_sel_hi:[1,0]
	v_pk_mul_f32 v[18:19], v[18:19], v[32:33] op_sel_hi:[1,0]
	v_pk_mul_f32 v[16:17], v[16:17], v[32:33] op_sel_hi:[1,0]
	v_pk_mul_f32 v[26:27], v[26:27], v[32:33] op_sel_hi:[1,0]
	v_pk_mul_f32 v[24:25], v[24:25], v[32:33] op_sel_hi:[1,0]
	v_pk_mul_f32 v[22:23], v[22:23], v[32:33] op_sel_hi:[1,0]
	v_pk_mul_f32 v[20:21], v[20:21], v[32:33] op_sel_hi:[1,0]
	v_pk_mul_f32 v[14:15], v[14:15], v[78:79] op_sel_hi:[1,0]
	v_pk_mul_f32 v[12:13], v[12:13], v[78:79] op_sel_hi:[1,0]
	v_pk_mul_f32 v[6:7], v[6:7], v[78:79] op_sel_hi:[1,0]
	v_pk_mul_f32 v[4:5], v[4:5], v[78:79] op_sel_hi:[1,0]
	v_pk_mul_f32 v[10:11], v[10:11], v[78:79] op_sel_hi:[1,0]
	v_pk_mul_f32 v[8:9], v[8:9], v[78:79] op_sel_hi:[1,0]
	v_pk_mul_f32 v[2:3], v[2:3], v[78:79] op_sel_hi:[1,0]
	v_pk_mul_f32 v[0:1], v[0:1], v[78:79] op_sel_hi:[1,0]

; template <int LO, int HI>
; __global__ void __launch_bounds__(NTHREADS) fwd_kernel(const Params p) {
	.amdhsa_kernel _Z10fwd_kernelILi0ELi5EEv6Params
		.amdhsa_group_segment_fixed_size 0
		.amdhsa_private_segment_fixed_size 0
		.amdhsa_kernarg_size 392
		.amdhsa_user_sgpr_count 2
		.amdhsa_user_sgpr_dispatch_ptr 0
		.amdhsa_user_sgpr_queue_ptr 0
		.amdhsa_user_sgpr_kernarg_segment_ptr 1
		.amdhsa_user_sgpr_dispatch_id 0
		.amdhsa_user_sgpr_kernarg_preload_length 0
		.amdhsa_user_sgpr_kernarg_preload_offset 0
		.amdhsa_user_sgpr_private_segment_size 0
		.amdhsa_uses_dynamic_stack 0
		.amdhsa_enable_private_segment 0
		.amdhsa_system_sgpr_workgroup_id_x 1
		.amdhsa_system_sgpr_workgroup_id_y 0
		.amdhsa_system_sgpr_workgroup_id_z 0
		.amdhsa_system_sgpr_workgroup_info 0
		.amdhsa_system_vgpr_workitem_id 2
		.amdhsa_next_free_vgpr 240
		.amdhsa_next_free_sgpr 98
		.amdhsa_accum_offset 240
		.amdhsa_reserve_vcc 1
		.amdhsa_float_round_mode_32 0
		.amdhsa_float_round_mode_16_64 0
		.amdhsa_float_denorm_mode_32 3
		.amdhsa_float_denorm_mode_16_64 3
		.amdhsa_dx10_clamp 1
		.amdhsa_ieee_mode 1
		.amdhsa_fp16_overflow 0
		.amdhsa_tg_split 0
		.amdhsa_exception_fp_ieee_invalid_op 0
		.amdhsa_exception_fp_denorm_src 0
		.amdhsa_exception_fp_ieee_div_zero 0
		.amdhsa_exception_fp_ieee_overflow 0
		.amdhsa_exception_fp_ieee_underflow 0
		.amdhsa_exception_fp_ieee_inexact 0
		.amdhsa_exception_int_div_zero 0
	.end_amdhsa_kernel

; template <int LO, int HI>
; __global__ void __launch_bounds__(NTHREADS) fwd_kernel(const Params p) {
amdhsa.kernels:
  - .agpr_count:     0
    .args:
      - .offset:         0
        .size:           136
        .value_kind:     by_value
      - .offset:         136
        .size:           4
        .value_kind:     hidden_block_count_x
      - .offset:         140
        .size:           4
        .value_kind:     hidden_block_count_y
      - .offset:         144
        .size:           4
        .value_kind:     hidden_block_count_z
      - .offset:         148
        .size:           2
        .value_kind:     hidden_group_size_x
      - .offset:         150
        .size:           2
        .value_kind:     hidden_group_size_y
      - .offset:         152
        .size:           2
        .value_kind:     hidden_group_size_z
      - .offset:         154
        .size:           2
        .value_kind:     hidden_remainder_x
      - .offset:         156
        .size:           2
        .value_kind:     hidden_remainder_y
      - .offset:         158
        .size:           2
        .value_kind:     hidden_remainder_z
      - .offset:         176
        .size:           8
        .value_kind:     hidden_global_offset_x
      - .offset:         184
        .size:           8
        .value_kind:     hidden_global_offset_y
      - .offset:         192
        .size:           8
        .value_kind:     hidden_global_offset_z
      - .offset:         200
        .size:           2
        .value_kind:     hidden_grid_dims
      - .offset:         224
        .size:           8
        .value_kind:     hidden_multigrid_sync_arg
      - .offset:         256
        .size:           4
        .value_kind:     hidden_dynamic_lds_size
    .group_segment_fixed_size: 0
    .kernarg_segment_align: 8
    .kernarg_segment_size: 392
    .language:       OpenCL C
    .language_version:
      - 2
      - 0
    .max_flat_workgroup_size: 512
    .name:           _Z10fwd_kernelILi0ELi5EEv6Params
    .private_segment_fixed_size: 0
    .sgpr_count:     104
    .sgpr_spill_count: 67
    .symbol:         _Z10fwd_kernelILi0ELi5EEv6Params.kd
    .uniform_work_group_size: 1
    .uses_dynamic_stack: false
    .vgpr_count:     240
    .vgpr_spill_count: 0
    .wavefront_size: 64
